# gd_task step loop unrolled x8 with 2 dot chains; interior-tile fast path in gd loader (no boundary masks); rw_task<2> loop as before
# speedup vs baseline: 1.0028x; 1.0028x over previous
; __device__ __forceinline__ h16x8 zeroh8() { h16x8 z; for (int i = 0; i < 8; ++i) z[i] = (h16)0.f; return z; }
; __device__ __forceinline__ void conv_silu8(const h16* pc, bool hp, bool hn, const float* cw, float* out) {
;     const h16x8 xc = ldh8(pc), xp = hp ? ldh8(pc - INC) : zeroh8(), xn = hn ? ldh8(pc + INC) : zeroh8();
;     const f32x4 w0a = *(const f32x4*)cw, w0b = *(const f32x4*)(cw + 4), w1a = *(const f32x4*)(cw + 3072), w1b = *(const f32x4*)(cw + 3076), w2a = *(const f32x4*)(cw + 6144), w2b = *(const f32x4*)(cw + 6148);
; __device__ __forceinline__ void gd_task(const Params& p, LAS unsigned char* shm, const int tid, const int s, const int d, const int h, const int rq) {
;     ...
;                     const int js = ti * TT + st, t = d ? T - 1 - js : js; const size_t m = (size_t)base + t;
;                     const h16* pr = P + m * INC + GDC; const bool hp = t > 0, hn = t < T - 1;
;                     const h16 bbv = pr[4096 + h], aav = pr[4104 + d * 8 + h];
;                     float q[16], k[16];
;                     conv_silu8(pr + qcol, hp, hn, p.gd_conv + qcol, q); conv_silu8(pr + qcol + 8, hp, hn, p.gd_conv + qcol + 8, q + 8);
;                     conv_silu8(pr + kcol, hp, hn, p.gd_conv + kcol, k); conv_silu8(pr + kcol + 8, hp, hn, p.gd_conv + kcol + 8, k + 8);
;                     float v[4];
;                     { const h16* pc = pr + vcol; const h16x4 xc = *(const h16x4*)pc, xp = hp ? *(const h16x4*)(pc - INC) : (h16x4){(h16)0.f, (h16)0.f, (h16)0.f, (h16)0.f}, xn = hn ? *(const h16x4*)(pc + INC) : (h16x4){(h16)0.f, (h16)0.f, (h16)0.f, (h16)0.f};
;                       const f32x4 a0 = *(const f32x4*)(p.gd_conv + vcol), a1 = *(const f32x4*)(p.gd_conv + 3072 + vcol), a2 = *(const f32x4*)(p.gd_conv + 6144 + vcol);
.LBB0_333:
	s_cmp_eq_u32 s4, 0x1ff
	s_cbranch_scc1 .Lgdl_slow
	v_add_u32_e32 v2, 64, v204
	v_subrev_u32_e32 v3, 64, v193
	v_cndmask_b32_e64 v7, v3, v2, s[40:41]
	v_add_u32_e32 v4, 0x8000, v7
	v_mov_b64_e32 v[2:3], s[26:27]
	v_mad_i64_i32 v[2:3], s[0:1], v4, s89, v[2:3]
	s_mov_b64 s[0:1], 0x12e05a80
	s_nop 0
	v_lshl_add_u64 v[184:185], v[2:3], 0, s[0:1]
	v_lshl_add_u64 v[2:3], v[184:185], 0, s[16:17]
	v_add_co_u32_e32 v2, vcc, s88, v2
	v_lshl_add_u64 v[4:5], s[48:49], 1, v[184:185]
	s_nop 0
	v_addc_co_u32_e32 v3, vcc, 0, v3, vcc
	v_mov_b32_e32 v149, v0
	v_lshl_add_u64 v[218:219], v[184:185], 0, v[148:149]
	global_load_ushort v199, v[2:3], off
	global_load_ushort v149, v[4:5], off
	s_nop 0
	global_load_dwordx4 v[2:5], v[218:219], off
	v_add_co_u32_e32 v208, vcc, 0xffffc550, v218
	s_nop 1
	v_addc_co_u32_e32 v209, vcc, -1, v219, vcc
	v_add_co_u32_e32 v210, vcc, 0x3ab0, v218
	s_nop 1
	v_addc_co_u32_e32 v211, vcc, 0, v219, vcc
	global_load_dwordx4 v[10:13], v[208:209], off
	global_load_dwordx4 v[6:9], v[210:211], off
	global_load_dwordx4 v[14:17], v[150:151], off offset:16
	global_load_dwordx4 v[26:29], v[150:151], off
	global_load_dwordx4 v[22:25], v[152:153], off offset:16
	global_load_dwordx4 v[34:37], v[152:153], off
	global_load_dwordx4 v[18:21], v[154:155], off offset:16
	global_load_dwordx4 v[30:33], v[154:155], off
	global_load_dwordx4 v[42:45], v[218:219], off offset:16
	global_load_dwordx4 v[46:49], v[208:209], off offset:16
	global_load_dwordx4 v[38:41], v[210:211], off offset:16
	global_load_dwordx4 v[54:57], v[150:151], off offset:48
	global_load_dwordx4 v[66:69], v[150:151], off offset:32
	global_load_dwordx4 v[58:61], v[156:157], off offset:16
	global_load_dwordx4 v[70:73], v[156:157], off
	global_load_dwordx4 v[50:53], v[158:159], off offset:16
	global_load_dwordx4 v[62:65], v[158:159], off
	global_load_dwordx4 v[78:81], v[218:219], off offset:2048
	global_load_dwordx4 v[82:85], v[208:209], off offset:2048
	global_load_dwordx4 v[74:77], v[210:211], off offset:2048
	global_load_dwordx4 v[90:93], v[164:165], off offset:16
	global_load_dwordx4 v[102:105], v[164:165], off
	global_load_dwordx4 v[94:97], v[166:167], off offset:16
	global_load_dwordx4 v[106:109], v[166:167], off
	global_load_dwordx4 v[86:89], v[168:169], off offset:16
	global_load_dwordx4 v[98:101], v[168:169], off
	global_load_dwordx4 v[114:117], v[218:219], off offset:2064
	global_load_dwordx4 v[118:121], v[208:209], off offset:2064
	global_load_dwordx4 v[110:113], v[210:211], off offset:2064
	global_load_dwordx4 v[126:129], v[164:165], off offset:48
	global_load_dwordx4 v[138:141], v[164:165], off offset:32
	global_load_dwordx4 v[130:133], v[170:171], off offset:16
	global_load_dwordx4 v[142:145], v[170:171], off
	global_load_dwordx4 v[122:125], v[172:173], off offset:16
	global_load_dwordx4 v[134:137], v[172:173], off
	v_mov_b32_e32 v175, v0
	v_lshl_add_u64 v[190:191], v[184:185], 0, v[174:175]
	global_load_dwordx2 v[186:187], v[190:191], off
	v_add_co_u32_e32 v214, vcc, 0xffffc550, v190
	s_nop 1
	v_addc_co_u32_e32 v215, vcc, -1, v191, vcc
	v_add_co_u32_e32 v216, vcc, 0x3ab0, v190
	s_nop 1
	v_addc_co_u32_e32 v217, vcc, 0, v191, vcc
	global_load_dwordx2 v[188:189], v[214:215], off
	global_load_dwordx2 v[184:185], v[216:217], off
	s_branch .Lgdl_join

; __device__ __forceinline__ float fsilu(float x) { return x * fsigmoid(x); }
; __device__ __forceinline__ h16x8 zeroh8() { h16x8 z; for (int i = 0; i < 8; ++i) z[i] = (h16)0.f; return z; }
; __device__ __forceinline__ void conv_silu8(const h16* pc, bool hp, bool hn, const float* cw, float* out) {
;     const h16x8 xc = ldh8(pc), xp = hp ? ldh8(pc - INC) : zeroh8(), xn = hn ? ldh8(pc + INC) : zeroh8();
;     const f32x4 w0a = *(const f32x4*)cw, w0b = *(const f32x4*)(cw + 4), w1a = *(const f32x4*)(cw + 3072), w1b = *(const f32x4*)(cw + 3076), w2a = *(const f32x4*)(cw + 6144), w2b = *(const f32x4*)(cw + 6148);
; #pragma unroll
;     for (int e = 0; e < 8; ++e) { const float a0 = e < 4 ? w0a[e & 3] : w0b[e & 3], a1 = e < 4 ? w1a[e & 3] : w1b[e & 3], a2 = e < 4 ? w2a[e & 3] : w2b[e & 3];
;         out[e] = fsilu((float)xp[e] * a0 + (float)xc[e] * a1 + (float)xn[e] * a2); }
; __device__ __forceinline__ void gd_task(const Params& p, LAS unsigned char* shm, const int tid, const int s, const int d, const int h, const int rq) {
;     ...
;                     conv_silu8(pr + qcol, hp, hn, p.gd_conv + qcol, q); conv_silu8(pr + qcol + 8, hp, hn, p.gd_conv + qcol + 8, q + 8);
;                     conv_silu8(pr + kcol, hp, hn, p.gd_conv + kcol, k); conv_silu8(pr + kcol + 8, hp, hn, p.gd_conv + kcol + 8, k + 8);
.Lgdl_join:
	s_waitcnt vmcnt(7)
	v_cvt_f32_f16_sdwa v207, v114 dst_sel:DWORD dst_unused:UNUSED_PAD src0_sel:WORD_1
	v_cvt_f32_f16_e32 v206, v114
	v_cvt_f32_f16_sdwa v191, v118 dst_sel:DWORD dst_unused:UNUSED_PAD src0_sel:WORD_1
	v_cvt_f32_f16_e32 v190, v118
	v_cvt_f32_f16_e32 v118, v115
	s_waitcnt vmcnt(3)
	v_pk_mul_f32 v[142:143], v[142:143], v[206:207]
	s_mov_b32 s0, 0x358637bd
	v_pk_fma_f32 v[138:139], v[138:139], v[190:191], v[142:143]
	v_cvt_f32_f16_sdwa v143, v110 dst_sel:DWORD dst_unused:UNUSED_PAD src0_sel:WORD_1
	v_cvt_f32_f16_e32 v142, v110
	s_bitcmp1_b32 s4, 0
	s_waitcnt vmcnt(1)
	v_pk_fma_f32 v[134:135], v[134:135], v[142:143], v[138:139]
	s_nop 0
	v_mul_f32_e32 v110, 0xbfb8aa3b, v134
	v_exp_f32_e32 v110, v110
	s_nop 0
	v_add_f32_e32 v110, 1.0, v110
	v_rcp_f32_e32 v138, v110
	v_mul_f32_e32 v110, 0xbfb8aa3b, v135
	v_exp_f32_e32 v110, v110
	s_nop 0
	v_add_f32_e32 v110, 1.0, v110
	v_rcp_f32_e32 v139, v110
	s_nop 0
	v_pk_mul_f32 v[134:135], v[134:135], v[138:139]
	v_cvt_f32_f16_sdwa v139, v119 dst_sel:DWORD dst_unused:UNUSED_PAD src0_sel:WORD_1
	v_cvt_f32_f16_e32 v138, v119
	v_cvt_f32_f16_sdwa v119, v115 dst_sel:DWORD dst_unused:UNUSED_PAD src0_sel:WORD_1
	v_pk_mul_f32 v[114:115], v[144:145], v[118:119]
	v_cvt_f32_f16_sdwa v119, v111 dst_sel:DWORD dst_unused:UNUSED_PAD src0_sel:WORD_1
	v_cvt_f32_f16_e32 v118, v111
	v_pk_fma_f32 v[114:115], v[140:141], v[138:139], v[114:115]
	s_nop 0
	v_pk_fma_f32 v[110:111], v[136:137], v[118:119], v[114:115]
	s_nop 0
	v_mul_f32_e32 v114, 0xbfb8aa3b, v110
	v_mul_f32_e32 v115, 0xbfb8aa3b, v111
	v_exp_f32_e32 v114, v114
	v_exp_f32_e32 v115, v115
	v_cvt_f32_f16_sdwa v119, v116 dst_sel:DWORD dst_unused:UNUSED_PAD src0_sel:WORD_1
	v_cvt_f32_f16_e32 v118, v116
	v_add_f32_e32 v114, 1.0, v114
	v_add_f32_e32 v115, 1.0, v115
	v_rcp_f32_e32 v114, v114
	v_rcp_f32_e32 v115, v115
	v_pk_mul_f32 v[118:119], v[130:131], v[118:119]
	v_pk_mul_f32 v[110:111], v[110:111], v[114:115]
	v_cvt_f32_f16_sdwa v115, v120 dst_sel:DWORD dst_unused:UNUSED_PAD src0_sel:WORD_1
	v_cvt_f32_f16_e32 v114, v120
	v_cvt_f32_f16_e32 v120, v117
	v_pk_fma_f32 v[114:115], v[126:127], v[114:115], v[118:119]
	v_cvt_f32_f16_sdwa v119, v112 dst_sel:DWORD dst_unused:UNUSED_PAD src0_sel:WORD_1
	v_cvt_f32_f16_e32 v118, v112
	v_pk_fma_f32 v[114:115], v[122:123], v[118:119], v[114:115]
	s_nop 0
	v_mul_f32_e32 v112, 0xbfb8aa3b, v114
	v_exp_f32_e32 v112, v112
	s_nop 0
	v_add_f32_e32 v112, 1.0, v112
	v_rcp_f32_e32 v118, v112
	v_mul_f32_e32 v112, 0xbfb8aa3b, v115
	v_exp_f32_e32 v112, v112
	s_nop 0
	v_add_f32_e32 v112, 1.0, v112
	v_rcp_f32_e32 v119, v112
	s_nop 0
	v_pk_mul_f32 v[114:115], v[114:115], v[118:119]
	v_cvt_f32_f16_sdwa v119, v121 dst_sel:DWORD dst_unused:UNUSED_PAD src0_sel:WORD_1
	v_cvt_f32_f16_e32 v118, v121
	v_cvt_f32_f16_sdwa v121, v117 dst_sel:DWORD dst_unused:UNUSED_PAD src0_sel:WORD_1
	v_pk_mul_f32 v[116:117], v[132:133], v[120:121]
	s_nop 0
	v_pk_fma_f32 v[116:117], v[128:129], v[118:119], v[116:117]
	v_cvt_f32_f16_sdwa v119, v113 dst_sel:DWORD dst_unused:UNUSED_PAD src0_sel:WORD_1
	v_cvt_f32_f16_e32 v118, v113
	v_pk_fma_f32 v[112:113], v[124:125], v[118:119], v[116:117]
	s_nop 0
	v_mul_f32_e32 v116, 0xbfb8aa3b, v112
	v_mul_f32_e32 v117, 0xbfb8aa3b, v113
	v_exp_f32_e32 v116, v116
	v_exp_f32_e32 v117, v117
	v_cvt_f32_f16_sdwa v119, v78 dst_sel:DWORD dst_unused:UNUSED_PAD src0_sel:WORD_1
	v_cvt_f32_f16_e32 v118, v78
	v_add_f32_e32 v116, 1.0, v116
	v_add_f32_e32 v117, 1.0, v117
	v_rcp_f32_e32 v116, v116
	v_rcp_f32_e32 v117, v117
	v_pk_mul_f32 v[106:107], v[106:107], v[118:119]
	v_pk_mul_f32 v[112:113], v[112:113], v[116:117]
	v_cvt_f32_f16_sdwa v117, v82 dst_sel:DWORD dst_unused:UNUSED_PAD src0_sel:WORD_1
	v_cvt_f32_f16_e32 v116, v82
	v_cvt_f32_f16_e32 v82, v79
	v_pk_fma_f32 v[102:103], v[102:103], v[116:117], v[106:107]
	v_cvt_f32_f16_sdwa v107, v74 dst_sel:DWORD dst_unused:UNUSED_PAD src0_sel:WORD_1
	v_cvt_f32_f16_e32 v106, v74
	v_pk_fma_f32 v[98:99], v[98:99], v[106:107], v[102:103]
	s_nop 0
	v_mul_f32_e32 v74, 0xbfb8aa3b, v98
	v_exp_f32_e32 v74, v74
	s_nop 0
	v_add_f32_e32 v74, 1.0, v74
	v_rcp_f32_e32 v102, v74
	v_mul_f32_e32 v74, 0xbfb8aa3b, v99
	v_exp_f32_e32 v74, v74
	s_nop 0
	v_add_f32_e32 v74, 1.0, v74
	v_rcp_f32_e32 v103, v74
	s_nop 0
	v_pk_mul_f32 v[98:99], v[98:99], v[102:103]
	v_cvt_f32_f16_sdwa v103, v83 dst_sel:DWORD dst_unused:UNUSED_PAD src0_sel:WORD_1
	v_cvt_f32_f16_e32 v102, v83
	v_cvt_f32_f16_sdwa v83, v79 dst_sel:DWORD dst_unused:UNUSED_PAD src0_sel:WORD_1
	v_pk_mul_f32 v[78:79], v[108:109], v[82:83]
	v_cvt_f32_f16_sdwa v83, v75 dst_sel:DWORD dst_unused:UNUSED_PAD src0_sel:WORD_1
	v_cvt_f32_f16_e32 v82, v75
	v_pk_fma_f32 v[78:79], v[104:105], v[102:103], v[78:79]
	s_nop 0
	v_pk_fma_f32 v[74:75], v[100:101], v[82:83], v[78:79]
	s_nop 0
	v_mul_f32_e32 v78, 0xbfb8aa3b, v74
	v_mul_f32_e32 v79, 0xbfb8aa3b, v75
	v_exp_f32_e32 v78, v78
	v_exp_f32_e32 v79, v79
	v_cvt_f32_f16_sdwa v83, v80 dst_sel:DWORD dst_unused:UNUSED_PAD src0_sel:WORD_1
	v_cvt_f32_f16_e32 v82, v80
	v_add_f32_e32 v78, 1.0, v78
	v_add_f32_e32 v79, 1.0, v79
	v_rcp_f32_e32 v78, v78
	v_rcp_f32_e32 v79, v79
	v_pk_mul_f32 v[82:83], v[94:95], v[82:83]
	v_pk_mul_f32 v[74:75], v[74:75], v[78:79]
	v_cvt_f32_f16_sdwa v79, v84 dst_sel:DWORD dst_unused:UNUSED_PAD src0_sel:WORD_1
	v_cvt_f32_f16_e32 v78, v84
	v_cvt_f32_f16_e32 v84, v81
	v_pk_fma_f32 v[78:79], v[90:91], v[78:79], v[82:83]
	v_cvt_f32_f16_sdwa v83, v76 dst_sel:DWORD dst_unused:UNUSED_PAD src0_sel:WORD_1
	v_cvt_f32_f16_e32 v82, v76
	v_pk_fma_f32 v[78:79], v[86:87], v[82:83], v[78:79]
	s_nop 0
	v_mul_f32_e32 v76, 0xbfb8aa3b, v78
	v_exp_f32_e32 v76, v76
	s_nop 0
	v_add_f32_e32 v76, 1.0, v76
	v_rcp_f32_e32 v82, v76
; __device__ __forceinline__ float fsilu(float x) { return x * fsigmoid(x); }
; __device__ __forceinline__ h16x8 zeroh8() { h16x8 z; for (int i = 0; i < 8; ++i) z[i] = (h16)0.f; return z; }
; __device__ __forceinline__ void conv_silu8(const h16* pc, bool hp, bool hn, const float* cw, float* out) {
;     const h16x8 xc = ldh8(pc), xp = hp ? ldh8(pc - INC) : zeroh8(), xn = hn ? ldh8(pc + INC) : zeroh8();
;     const f32x4 w0a = *(const f32x4*)cw, w0b = *(const f32x4*)(cw + 4), w1a = *(const f32x4*)(cw + 3072), w1b = *(const f32x4*)(cw + 3076), w2a = *(const f32x4*)(cw + 6144), w2b = *(const f32x4*)(cw + 6148);
; #pragma unroll
;     for (int e = 0; e < 8; ++e) { const float a0 = e < 4 ? w0a[e & 3] : w0b[e & 3], a1 = e < 4 ? w1a[e & 3] : w1b[e & 3], a2 = e < 4 ? w2a[e & 3] : w2b[e & 3];
;         out[e] = fsilu((float)xp[e] * a0 + (float)xc[e] * a1 + (float)xn[e] * a2); }
; __device__ __forceinline__ void gd_task(const Params& p, LAS unsigned char* shm, const int tid, const int s, const int d, const int h, const int rq) {
;     ...
;                       for (int e = 0; e < 4; ++e) v[e] = fsilu((float)xp[e] * a0[e] + (float)xc[e] * a1[e] + (float)xn[e] * a2[e]); }
;                     float nq = 0.f, nk = 0.f;
; #pragma unroll
;                     for (int e = 0; e < 16; ++e) { nq += q[e] * q[e]; nk += k[e] * k[e]; }
	v_mul_f32_e32 v76, 0xbfb8aa3b, v79
	v_exp_f32_e32 v76, v76
	s_nop 0
	v_add_f32_e32 v76, 1.0, v76
	v_rcp_f32_e32 v83, v76
	s_nop 0
	v_pk_mul_f32 v[78:79], v[78:79], v[82:83]
	v_cvt_f32_f16_sdwa v83, v85 dst_sel:DWORD dst_unused:UNUSED_PAD src0_sel:WORD_1
	v_cvt_f32_f16_e32 v82, v85
	v_cvt_f32_f16_sdwa v85, v81 dst_sel:DWORD dst_unused:UNUSED_PAD src0_sel:WORD_1
	v_pk_mul_f32 v[80:81], v[96:97], v[84:85]
	s_nop 0
	v_pk_fma_f32 v[80:81], v[92:93], v[82:83], v[80:81]
	v_cvt_f32_f16_sdwa v83, v77 dst_sel:DWORD dst_unused:UNUSED_PAD src0_sel:WORD_1
	v_cvt_f32_f16_e32 v82, v77
	v_pk_fma_f32 v[76:77], v[88:89], v[82:83], v[80:81]
	s_nop 0
	v_mul_f32_e32 v80, 0xbfb8aa3b, v76
	v_mul_f32_e32 v81, 0xbfb8aa3b, v77
	v_exp_f32_e32 v80, v80
	v_exp_f32_e32 v81, v81
	v_cvt_f32_f16_sdwa v83, v42 dst_sel:DWORD dst_unused:UNUSED_PAD src0_sel:WORD_1
	v_cvt_f32_f16_e32 v82, v42
	v_add_f32_e32 v80, 1.0, v80
	v_add_f32_e32 v81, 1.0, v81
	v_rcp_f32_e32 v80, v80
	v_rcp_f32_e32 v81, v81
	v_pk_mul_f32 v[70:71], v[70:71], v[82:83]
	v_pk_mul_f32 v[76:77], v[76:77], v[80:81]
	v_cvt_f32_f16_sdwa v81, v46 dst_sel:DWORD dst_unused:UNUSED_PAD src0_sel:WORD_1
	v_cvt_f32_f16_e32 v80, v46
	v_cvt_f32_f16_e32 v46, v43
	v_pk_fma_f32 v[66:67], v[66:67], v[80:81], v[70:71]
	v_cvt_f32_f16_sdwa v71, v38 dst_sel:DWORD dst_unused:UNUSED_PAD src0_sel:WORD_1
	v_cvt_f32_f16_e32 v70, v38
	v_pk_fma_f32 v[62:63], v[62:63], v[70:71], v[66:67]
	s_nop 0
	v_mul_f32_e32 v38, 0xbfb8aa3b, v62
	v_exp_f32_e32 v38, v38
	s_nop 0
	v_add_f32_e32 v38, 1.0, v38
	v_rcp_f32_e32 v66, v38
	v_mul_f32_e32 v38, 0xbfb8aa3b, v63
	v_exp_f32_e32 v38, v38
	s_nop 0
	v_add_f32_e32 v38, 1.0, v38
	v_rcp_f32_e32 v67, v38
	s_nop 0
	v_pk_mul_f32 v[62:63], v[62:63], v[66:67]
	v_cvt_f32_f16_sdwa v67, v47 dst_sel:DWORD dst_unused:UNUSED_PAD src0_sel:WORD_1
	v_cvt_f32_f16_e32 v66, v47
	v_cvt_f32_f16_sdwa v47, v43 dst_sel:DWORD dst_unused:UNUSED_PAD src0_sel:WORD_1
	v_pk_mul_f32 v[42:43], v[72:73], v[46:47]
	v_cvt_f32_f16_sdwa v47, v39 dst_sel:DWORD dst_unused:UNUSED_PAD src0_sel:WORD_1
	v_cvt_f32_f16_e32 v46, v39
	v_pk_fma_f32 v[42:43], v[68:69], v[66:67], v[42:43]
	s_nop 0
	v_pk_fma_f32 v[38:39], v[64:65], v[46:47], v[42:43]
	s_nop 0
	v_mul_f32_e32 v42, 0xbfb8aa3b, v38
	v_mul_f32_e32 v43, 0xbfb8aa3b, v39
	v_exp_f32_e32 v42, v42
	v_exp_f32_e32 v43, v43
	v_cvt_f32_f16_sdwa v47, v44 dst_sel:DWORD dst_unused:UNUSED_PAD src0_sel:WORD_1
	v_cvt_f32_f16_e32 v46, v44
	v_add_f32_e32 v42, 1.0, v42
	v_add_f32_e32 v43, 1.0, v43
	v_rcp_f32_e32 v42, v42
	v_rcp_f32_e32 v43, v43
	v_pk_mul_f32 v[46:47], v[58:59], v[46:47]
	v_pk_mul_f32 v[38:39], v[38:39], v[42:43]
	v_cvt_f32_f16_sdwa v43, v48 dst_sel:DWORD dst_unused:UNUSED_PAD src0_sel:WORD_1
	v_cvt_f32_f16_e32 v42, v48
	v_cvt_f32_f16_e32 v48, v45
	v_pk_fma_f32 v[42:43], v[54:55], v[42:43], v[46:47]
	v_cvt_f32_f16_sdwa v47, v40 dst_sel:DWORD dst_unused:UNUSED_PAD src0_sel:WORD_1
	v_cvt_f32_f16_e32 v46, v40
	v_pk_fma_f32 v[42:43], v[50:51], v[46:47], v[42:43]
	s_nop 0
	v_mul_f32_e32 v40, 0xbfb8aa3b, v42
	v_exp_f32_e32 v40, v40
	s_nop 0
	v_add_f32_e32 v40, 1.0, v40
	v_rcp_f32_e32 v46, v40
	v_mul_f32_e32 v40, 0xbfb8aa3b, v43
	v_exp_f32_e32 v40, v40
	s_nop 0
	v_add_f32_e32 v40, 1.0, v40
	v_rcp_f32_e32 v47, v40
	s_nop 0
	v_pk_mul_f32 v[42:43], v[42:43], v[46:47]
	v_cvt_f32_f16_sdwa v47, v49 dst_sel:DWORD dst_unused:UNUSED_PAD src0_sel:WORD_1
	v_cvt_f32_f16_e32 v46, v49
	v_cvt_f32_f16_sdwa v49, v45 dst_sel:DWORD dst_unused:UNUSED_PAD src0_sel:WORD_1
	v_pk_mul_f32 v[44:45], v[60:61], v[48:49]
	s_nop 0
	v_pk_fma_f32 v[44:45], v[56:57], v[46:47], v[44:45]
	v_cvt_f32_f16_sdwa v47, v41 dst_sel:DWORD dst_unused:UNUSED_PAD src0_sel:WORD_1
	v_cvt_f32_f16_e32 v46, v41
	v_pk_fma_f32 v[40:41], v[52:53], v[46:47], v[44:45]
	s_nop 0
	v_mul_f32_e32 v44, 0xbfb8aa3b, v40
	v_mul_f32_e32 v45, 0xbfb8aa3b, v41
	v_exp_f32_e32 v44, v44
	v_exp_f32_e32 v45, v45
	v_cvt_f32_f16_sdwa v47, v2 dst_sel:DWORD dst_unused:UNUSED_PAD src0_sel:WORD_1
	v_cvt_f32_f16_e32 v46, v2
	v_add_f32_e32 v44, 1.0, v44
	v_add_f32_e32 v45, 1.0, v45
	v_rcp_f32_e32 v44, v44
	v_rcp_f32_e32 v45, v45
	v_pk_mul_f32 v[34:35], v[34:35], v[46:47]
	v_pk_mul_f32 v[40:41], v[40:41], v[44:45]
	v_cvt_f32_f16_sdwa v45, v10 dst_sel:DWORD dst_unused:UNUSED_PAD src0_sel:WORD_1
	v_cvt_f32_f16_e32 v44, v10
	v_cvt_f32_f16_e32 v10, v3
	v_pk_fma_f32 v[26:27], v[26:27], v[44:45], v[34:35]
	v_cvt_f32_f16_sdwa v35, v6 dst_sel:DWORD dst_unused:UNUSED_PAD src0_sel:WORD_1
	v_cvt_f32_f16_e32 v34, v6
	v_pk_fma_f32 v[26:27], v[30:31], v[34:35], v[26:27]
	s_nop 0
	v_mul_f32_e32 v2, 0xbfb8aa3b, v26
	v_exp_f32_e32 v2, v2
	s_nop 0
	v_add_f32_e32 v2, 1.0, v2
	v_rcp_f32_e32 v30, v2
	v_mul_f32_e32 v2, 0xbfb8aa3b, v27
	v_exp_f32_e32 v2, v2
	s_nop 0
	v_add_f32_e32 v2, 1.0, v2
	v_rcp_f32_e32 v31, v2
	s_nop 0
	v_pk_mul_f32 v[26:27], v[26:27], v[30:31]
	v_cvt_f32_f16_sdwa v31, v11 dst_sel:DWORD dst_unused:UNUSED_PAD src0_sel:WORD_1
	v_cvt_f32_f16_e32 v30, v11
	v_cvt_f32_f16_sdwa v11, v3 dst_sel:DWORD dst_unused:UNUSED_PAD src0_sel:WORD_1
	v_pk_mul_f32 v[2:3], v[36:37], v[10:11]
	v_cvt_f32_f16_sdwa v11, v7 dst_sel:DWORD dst_unused:UNUSED_PAD src0_sel:WORD_1
	v_cvt_f32_f16_e32 v10, v7
	v_pk_fma_f32 v[2:3], v[28:29], v[30:31], v[2:3]
	v_pk_mul_f32 v[30:31], v[40:41], v[40:41]
	v_pk_fma_f32 v[2:3], v[32:33], v[10:11], v[2:3]
	s_nop 0
	v_mul_f32_e32 v6, 0xbfb8aa3b, v2
	v_mul_f32_e32 v7, 0xbfb8aa3b, v3
	v_exp_f32_e32 v6, v6
	v_exp_f32_e32 v7, v7
	v_pk_mul_f32 v[32:33], v[112:113], v[112:113]
	v_add_f32_e32 v6, 1.0, v6
	v_add_f32_e32 v7, 1.0, v7
	v_rcp_f32_e32 v6, v6
	v_rcp_f32_e32 v7, v7
	s_nop 0
	v_pk_mul_f32 v[28:29], v[2:3], v[6:7]
	v_cvt_f32_f16_sdwa v7, v4 dst_sel:DWORD dst_unused:UNUSED_PAD src0_sel:WORD_1
	v_cvt_f32_f16_e32 v6, v4
	v_cvt_f32_f16_sdwa v3, v12 dst_sel:DWORD dst_unused:UNUSED_PAD src0_sel:WORD_1
	v_cvt_f32_f16_e32 v2, v12
	v_pk_mul_f32 v[6:7], v[22:23], v[6:7]
	v_pk_mul_f32 v[22:23], v[42:43], v[42:43]
	v_pk_fma_f32 v[2:3], v[14:15], v[2:3], v[6:7]
	v_cvt_f32_f16_sdwa v7, v8 dst_sel:DWORD dst_unused:UNUSED_PAD src0_sel:WORD_1
	v_cvt_f32_f16_e32 v6, v8
	v_pk_fma_f32 v[2:3], v[18:19], v[6:7], v[2:3]
	s_nop 0
	v_mul_f32_e32 v4, 0xbfb8aa3b, v2
	v_exp_f32_e32 v4, v4
	s_waitcnt vmcnt(0)
; __device__ __forceinline__ float fsilu(float x) { return x * fsigmoid(x); }
; __device__ __forceinline__ void gd_task(const Params& p, LAS unsigned char* shm, const int tid, const int s, const int d, const int h, const int rq) {
;     ...
;                     { const h16* pc = pr + vcol; const h16x4 xc = *(const h16x4*)pc, xp = hp ? *(const h16x4*)(pc - INC) : (h16x4){(h16)0.f, (h16)0.f, (h16)0.f, (h16)0.f}, xn = hn ? *(const h16x4*)(pc + INC) : (h16x4){(h16)0.f, (h16)0.f, (h16)0.f, (h16)0.f};
;                       const f32x4 a0 = *(const f32x4*)(p.gd_conv + vcol), a1 = *(const f32x4*)(p.gd_conv + 3072 + vcol), a2 = *(const f32x4*)(p.gd_conv + 6144 + vcol);
; #pragma unroll
;                       for (int e = 0; e < 4; ++e) v[e] = fsilu((float)xp[e] * a0[e] + (float)xc[e] * a1[e] + (float)xn[e] * a2[e]); }
;                     float nq = 0.f, nk = 0.f;
; #pragma unroll
;                     for (int e = 0; e < 16; ++e) { nq += q[e] * q[e]; nk += k[e] * k[e]; }
;                     nq = red8(nq); nk = red8(nk);
;                     const float rq_ = rsqrtf(nq + 1e-6f) * 0.08838834764831845f, rk_ = rsqrtf(nk + 1e-6f);
;                     float kq = 0.f;
; #pragma unroll
;                     for (int e = 0; e < 16; ++e) { q[e] *= rq_; k[e] *= rk_; kq += q[e] * k[e]; }
	v_cvt_f32_f16_sdwa v19, v188 dst_sel:DWORD dst_unused:UNUSED_PAD src0_sel:WORD_1
	v_cvt_f32_f16_e32 v18, v188
	v_add_f32_e32 v4, 1.0, v4
	v_rcp_f32_e32 v6, v4
	v_mul_f32_e32 v4, 0xbfb8aa3b, v3
	v_exp_f32_e32 v4, v4
	s_nop 0
	v_add_f32_e32 v4, 1.0, v4
	v_rcp_f32_e32 v7, v4
	s_nop 0
	v_pk_mul_f32 v[14:15], v[2:3], v[6:7]
	v_cvt_f32_f16_sdwa v7, v5 dst_sel:DWORD dst_unused:UNUSED_PAD src0_sel:WORD_1
	v_cvt_f32_f16_e32 v6, v5
	v_cvt_f32_f16_sdwa v3, v13 dst_sel:DWORD dst_unused:UNUSED_PAD src0_sel:WORD_1
	v_cvt_f32_f16_e32 v2, v13
	v_pk_mul_f32 v[4:5], v[24:25], v[6:7]
	v_pk_mul_f32 v[24:25], v[114:115], v[114:115]
	v_pk_fma_f32 v[2:3], v[16:17], v[2:3], v[4:5]
	v_cvt_f32_f16_sdwa v5, v9 dst_sel:DWORD dst_unused:UNUSED_PAD src0_sel:WORD_1
	v_cvt_f32_f16_e32 v4, v9
	v_pk_fma_f32 v[2:3], v[20:21], v[4:5], v[2:3]
	s_nop 0
	v_mul_f32_e32 v4, 0xbfb8aa3b, v2
	v_mul_f32_e32 v5, 0xbfb8aa3b, v3
	v_exp_f32_e32 v4, v4
	v_exp_f32_e32 v5, v5
	v_cvt_f32_f16_sdwa v21, v186 dst_sel:DWORD dst_unused:UNUSED_PAD src0_sel:WORD_1
	v_cvt_f32_f16_e32 v20, v186
	v_add_f32_e32 v4, 1.0, v4
	v_add_f32_e32 v5, 1.0, v5
	v_rcp_f32_e32 v4, v4
	v_rcp_f32_e32 v5, v5
	s_nop 0
	v_pk_mul_f32 v[16:17], v[2:3], v[4:5]
	global_load_dwordx4 v[2:5], v[176:177], off
	global_load_dwordx4 v[10:13], v[178:179], off
	global_load_dwordx4 v[6:9], v[180:181], off
	s_waitcnt vmcnt(1)
	v_pk_mul_f32 v[10:11], v[10:11], v[20:21]
	s_nop 0
	v_pk_fma_f32 v[2:3], v[2:3], v[18:19], v[10:11]
	v_cvt_f32_f16_sdwa v11, v184 dst_sel:DWORD dst_unused:UNUSED_PAD src0_sel:WORD_1
	v_cvt_f32_f16_e32 v10, v184
	v_cvt_f32_f16_sdwa v19, v187 dst_sel:DWORD dst_unused:UNUSED_PAD src0_sel:WORD_1
	v_cvt_f32_f16_e32 v18, v187
	v_pk_mul_f32 v[20:21], v[110:111], v[110:111]
	s_waitcnt vmcnt(0)
	v_pk_fma_f32 v[2:3], v[6:7], v[10:11], v[2:3]
	v_cvt_f32_f16_sdwa v11, v189 dst_sel:DWORD dst_unused:UNUSED_PAD src0_sel:WORD_1
	v_cvt_f32_f16_e32 v10, v189
	v_pk_mul_f32 v[12:13], v[12:13], v[18:19]
	v_mov_b32_e32 v18, v99
	v_mov_b32_e32 v19, v27
	v_pk_fma_f32 v[4:5], v[4:5], v[10:11], v[12:13]
	v_cvt_f32_f16_sdwa v11, v185 dst_sel:DWORD dst_unused:UNUSED_PAD src0_sel:WORD_1
	v_cvt_f32_f16_e32 v10, v185
	v_mov_b32_e32 v12, v98
	v_mov_b32_e32 v13, v26
	v_pk_mul_f32 v[18:19], v[18:19], v[18:19]
	v_pk_fma_f32 v[4:5], v[8:9], v[10:11], v[4:5]
	v_pk_fma_f32 v[12:13], v[12:13], v[12:13], v[18:19]
	v_mul_f32_e32 v8, 0xbfb8aa3b, v4
	v_exp_f32_e32 v8, v8
	v_mov_b32_e32 v18, v74
	v_mov_b32_e32 v19, v28
	v_pk_fma_f32 v[12:13], v[18:19], v[18:19], v[12:13]
	v_add_f32_e32 v8, 1.0, v8
	v_rcp_f32_e32 v46, v8
	v_mul_f32_e32 v8, 0xbfb8aa3b, v5
	v_exp_f32_e32 v8, v8
	v_mov_b32_e32 v18, v75
	v_mov_b32_e32 v19, v29
	v_pk_fma_f32 v[12:13], v[18:19], v[18:19], v[12:13]
	v_mov_b32_e32 v18, v78
	v_mov_b32_e32 v19, v14
	v_pk_fma_f32 v[12:13], v[18:19], v[18:19], v[12:13]
	v_mov_b32_e32 v18, v79
	v_mov_b32_e32 v19, v15
	v_add_f32_e32 v8, 1.0, v8
	v_pk_fma_f32 v[12:13], v[18:19], v[18:19], v[12:13]
	v_mov_b32_e32 v18, v76
	v_mov_b32_e32 v19, v16
	v_rcp_f32_e32 v47, v8
	v_pk_mul_f32 v[8:9], v[62:63], v[62:63]
	v_pk_mul_f32 v[10:11], v[134:135], v[134:135]
	v_pk_fma_f32 v[12:13], v[18:19], v[18:19], v[12:13]
	v_mov_b32_e32 v18, v77
	v_mov_b32_e32 v19, v17
	v_pk_fma_f32 v[12:13], v[18:19], v[18:19], v[12:13]
	v_mov_b32_e32 v18, v10
	v_mov_b32_e32 v19, v8
	v_pk_add_f32 v[12:13], v[12:13], v[18:19]
	v_pk_mul_f32 v[18:19], v[38:39], v[38:39]
	v_mov_b32_e32 v8, v11
	v_pk_add_f32 v[8:9], v[8:9], v[12:13]
	v_mov_b32_e32 v10, v20
	v_mov_b32_e32 v11, v18
	v_pk_add_f32 v[8:9], v[10:11], v[8:9]
	v_mov_b32_e32 v18, v21
	v_pk_add_f32 v[8:9], v[18:19], v[8:9]
	v_mov_b32_e32 v10, v24
	v_mov_b32_e32 v11, v22
	v_pk_add_f32 v[8:9], v[10:11], v[8:9]
	v_mov_b32_e32 v22, v25
	v_pk_add_f32 v[8:9], v[22:23], v[8:9]
	v_mov_b32_e32 v10, v32
	v_mov_b32_e32 v11, v30
	v_pk_add_f32 v[8:9], v[10:11], v[8:9]
	v_mov_b32_e32 v30, v33
	v_pk_add_f32 v[8:9], v[30:31], v[8:9]
	v_mul_f32_e32 v6, 0xbfb8aa3b, v2
	v_mul_f32_e32 v7, 0xbfb8aa3b, v3
	v_mov_b32_dpp v11, v9 quad_perm:[1,0,3,2] row_mask:0xf bank_mask:0xf bound_ctrl:1
	v_mov_b32_dpp v10, v8 quad_perm:[1,0,3,2] row_mask:0xf bank_mask:0xf bound_ctrl:1
	v_pk_add_f32 v[8:9], v[8:9], v[10:11]
	v_exp_f32_e32 v6, v6
	v_exp_f32_e32 v7, v7
	v_mov_b32_dpp v11, v9 quad_perm:[2,3,0,1] row_mask:0xf bank_mask:0xf bound_ctrl:1
	v_mov_b32_dpp v10, v8 quad_perm:[2,3,0,1] row_mask:0xf bank_mask:0xf bound_ctrl:1
	v_pk_add_f32 v[8:9], v[8:9], v[10:11]
	v_add_f32_e32 v6, 1.0, v6
	v_add_f32_e32 v7, 1.0, v7
	v_mov_b32_dpp v11, v9 row_half_mirror row_mask:0xf bank_mask:0xf bound_ctrl:1
	v_mov_b32_dpp v10, v8 row_half_mirror row_mask:0xf bank_mask:0xf bound_ctrl:1
	v_pk_add_f32 v[8:9], v[8:9], v[10:11]
	v_rcp_f32_e32 v6, v6
	v_pk_add_f32 v[8:9], v[8:9], s[0:1] op_sel_hi:[1,0]
	v_rcp_f32_e32 v7, v7
	v_mul_f32_e32 v10, 0x4b800000, v9
	v_cmp_gt_f32_e64 s[0:1], s86, v9
	v_cmp_gt_f32_e32 vcc, s86, v8
	v_pk_mul_f32 v[2:3], v[2:3], v[6:7]
	v_cndmask_b32_e64 v9, v9, v10, s[0:1]
	v_rsq_f32_e32 v9, v9
	v_pk_mul_f32 v[4:5], v[4:5], v[46:47]
	v_mul_f32_e32 v10, 0x45800000, v9
	v_cndmask_b32_e64 v9, v9, v10, s[0:1]
	v_mul_f32_e32 v10, 0x3db504f3, v9
	v_mul_f32_e32 v9, 0x4b800000, v8
	v_cndmask_b32_e32 v8, v8, v9, vcc
	v_rsq_f32_e32 v8, v8
	v_pk_mul_f32 v[18:19], v[26:27], v[10:11] op_sel_hi:[1,0]
	v_pk_mul_f32 v[20:21], v[28:29], v[10:11] op_sel_hi:[1,0]
	v_pk_mul_f32 v[30:31], v[62:63], v[10:11] op_sel_hi:[1,0]
	v_mul_f32_e32 v9, 0x45800000, v8
	v_cndmask_b32_e32 v8, v8, v9, vcc
	v_pk_mul_f32 v[22:23], v[98:99], v[8:9] op_sel_hi:[1,0]
	v_pk_mul_f32 v[32:33], v[38:39], v[10:11] op_sel_hi:[1,0]
	v_pk_mul_f32 v[12:13], v[18:19], v[22:23]
	v_pk_mul_f32 v[38:39], v[42:43], v[10:11] op_sel_hi:[1,0]
; #define LAS __attribute__((address_space(3)))
; __device__ __forceinline__ float softplusf_(float x) { return fmaxf(x, 0.f) + log1pf(expf(-fabsf(x))); }
; __device__ __forceinline__ float fsigmoid(float x) { return __builtin_amdgcn_rcpf(1.0f + __expf(-x)); }
; __device__ __forceinline__ void gd_task(const Params& p, LAS unsigned char* shm, const int tid, const int s, const int d, const int h, const int rq) {
;     ...
;                     float kq = 0.f;
; #pragma unroll
;                     for (int e = 0; e < 16; ++e) { q[e] *= rq_; k[e] *= rk_; kq += q[e] * k[e]; }
;                     kq = red8(kq);
;                     LAS float* sb = inb + (ti & 1) * GD_INF + st * GD_STRIDE;
; #pragma unroll
;                     for (int e = 0; e < 4; ++e) { *(LAS f32x4*)(sb + 20 * jj + 4 * e) = (f32x4){k[4 * e], k[4 * e + 1], k[4 * e + 2], k[4 * e + 3]};
;                         *(LAS f32x4*)(sb + 160 + 20 * jj + 4 * e) = (f32x4){q[4 * e], q[4 * e + 1], q[4 * e + 2], q[4 * e + 3]}; }
;                     *(LAS f32x4*)(sb + 320 + 4 * jj) = (f32x4){v[0], v[1], v[2], v[3]};
;                     if (jj == 0) { const float beta = fsigmoid((float)bbv); const float ain = (float)aav;
;                         const float g = alog * softplusf_(ain + dtb); const float wdec = __expf(g);
;                         *(LAS f32x4*)(sb + 352) = (f32x4){wdec, wdec * beta, kq, beta}; }
	v_add_f32_e32 v9, 0, v12
	v_add_f32_e32 v9, v13, v9
	v_pk_mul_f32 v[24:25], v[74:75], v[8:9] op_sel_hi:[1,0]
	s_cselect_b32 s0, 0xb200, 0
	v_pk_mul_f32 v[12:13], v[20:21], v[24:25]
	s_nop 0
	v_add_f32_e32 v9, v12, v9
	v_add_f32_e32 v9, v13, v9
	v_pk_mul_f32 v[12:13], v[14:15], v[10:11] op_sel_hi:[1,0]
	v_pk_mul_f32 v[26:27], v[78:79], v[8:9] op_sel_hi:[1,0]
	s_nop 0
	v_pk_mul_f32 v[14:15], v[12:13], v[26:27]
	s_nop 0
	v_add_f32_e32 v9, v14, v9
	v_add_f32_e32 v9, v15, v9
	v_pk_mul_f32 v[14:15], v[16:17], v[10:11] op_sel_hi:[1,0]
	v_pk_mul_f32 v[28:29], v[76:77], v[8:9] op_sel_hi:[1,0]
	s_nop 0
	v_pk_mul_f32 v[16:17], v[14:15], v[28:29]
	s_nop 0
	v_add_f32_e32 v9, v16, v9
	v_add_f32_e32 v9, v17, v9
	v_pk_mul_f32 v[34:35], v[134:135], v[8:9] op_sel_hi:[1,0]
	s_nop 0
	v_pk_mul_f32 v[16:17], v[30:31], v[34:35]
	s_nop 0
	v_add_f32_e32 v9, v16, v9
	v_add_f32_e32 v9, v17, v9
	v_pk_mul_f32 v[36:37], v[110:111], v[8:9] op_sel_hi:[1,0]
	s_nop 0
	v_pk_mul_f32 v[16:17], v[32:33], v[36:37]
	s_nop 0
	v_add_f32_e32 v9, v16, v9
	v_add_f32_e32 v9, v17, v9
	v_pk_mul_f32 v[42:43], v[114:115], v[8:9] op_sel_hi:[1,0]
	s_nop 0
	v_pk_mul_f32 v[16:17], v[38:39], v[42:43]
	s_nop 0
	v_add_f32_e32 v9, v16, v9
	v_add_f32_e32 v11, v17, v9
	v_pk_mul_f32 v[40:41], v[40:41], v[10:11] op_sel_hi:[1,0]
	v_pk_mul_f32 v[44:45], v[112:113], v[8:9] op_sel_hi:[1,0]
	s_nop 0
	v_pk_mul_f32 v[8:9], v[40:41], v[44:45]
	s_nop 0
	v_add_f32_e32 v8, v8, v11
	v_add_f32_e32 v8, v9, v8
	s_nop 1
	v_add_f32_dpp v8, v8, v8 quad_perm:[1,0,3,2] row_mask:0xf bank_mask:0xf bound_ctrl:1
	s_nop 1
	v_add_f32_dpp v9, v8, v8 quad_perm:[2,3,0,1] row_mask:0xf bank_mask:0xf bound_ctrl:1
	v_add_u32_e32 v8, s0, v196
	v_lshl_add_u32 v11, v200, 2, v8
	v_mov_b32_dpp v10, v9 row_half_mirror row_mask:0xf bank_mask:0xf bound_ctrl:1
	v_add_u32_e32 v6, v11, v201
	ds_write_b128 v11, v[22:25]
	ds_write_b128 v11, v[18:21] offset:640
	ds_write_b128 v11, v[26:29] offset:16
	ds_write_b128 v11, v[12:15] offset:656
	ds_write_b128 v11, v[34:37] offset:32
	ds_write_b128 v11, v[30:33] offset:672
	ds_write_b128 v11, v[42:45] offset:48
	ds_write_b128 v11, v[38:41] offset:688
	ds_write_b128 v6, v[2:5] offset:1280
	s_and_saveexec_b64 s[0:1], s[42:43]
	s_cbranch_execz .LBB0_332
	v_cvt_f32_f16_e32 v2, v199
	s_mov_b32 s6, 0xbfb8aa3b
	v_add_f32_e32 v4, v9, v10
	v_mul_f32_e32 v2, 0xbfb8aa3b, v2
	v_exp_f32_e32 v2, v2
	s_nop 0
	v_add_f32_e32 v2, 1.0, v2
	v_rcp_f32_e32 v5, v2
	v_cvt_f32_f16_e32 v2, v149
	v_add_f32_e32 v2, v192, v2
	v_mul_f32_e64 v3, |v2|, s6
	v_fma_f32 v6, |v2|, s6, -v3
	s_mov_b32 s6, 0xb2a5705f
	v_rndne_f32_e32 v7, v3
	v_fma_f32 v6, |v2|, s6, v6
	v_sub_f32_e32 v3, v3, v7
	v_add_f32_e32 v3, v3, v6
	v_exp_f32_e32 v3, v3
	v_cvt_i32_f32_e32 v6, v7
	s_mov_b32 s6, 0x42ce8ed0
	v_cmp_ngt_f32_e64 vcc, |v2|, s6
	s_mov_b32 s6, 0xc2b17218
	v_ldexp_f32 v3, v3, v6
	v_cndmask_b32_e32 v3, 0, v3, vcc
	v_cmp_nlt_f32_e64 vcc, |v2|, s6
	v_max_f32_e32 v9, 0, v2
	s_mov_b32 s6, 0x3f2aaaab
	v_cndmask_b32_e32 v20, v233, v3, vcc
	v_add_f32_e32 v6, 1.0, v20
	v_add_f32_e32 v2, -1.0, v6
	v_sub_f32_e32 v3, v2, v6
	v_add_f32_e32 v3, 1.0, v3
	v_sub_f32_e32 v2, v20, v2
	v_add_f32_e32 v7, v2, v3
	v_frexp_mant_f32_e32 v2, v6
	v_cmp_gt_f32_e32 vcc, s6, v2
	v_cvt_f64_f32_e32 v[2:3], v6
	v_frexp_exp_i32_f64_e32 v2, v[2:3]
	v_subbrev_co_u32_e32 v14, vcc, 0, v2, vcc
	v_sub_u32_e32 v2, 0, v14
	v_ldexp_f32 v3, v6, v2
	v_add_f32_e32 v6, -1.0, v3
	v_add_f32_e32 v10, 1.0, v3
	v_ldexp_f32 v2, v7, v2
	v_add_f32_e32 v7, 1.0, v6
	v_add_f32_e32 v11, -1.0, v10
	v_sub_f32_e32 v7, v3, v7
	v_sub_f32_e32 v3, v3, v11
	v_add_f32_e32 v7, v2, v7
	v_add_f32_e32 v2, v2, v3
	v_add_f32_e32 v15, v10, v2
	v_rcp_f32_e32 v17, v15
	v_sub_f32_e32 v3, v10, v15
	v_add_f32_e32 v16, v2, v3
	v_add_f32_e32 v3, v6, v7
	v_mul_f32_e32 v19, v3, v17
	v_sub_f32_e32 v2, v6, v3
	v_mul_f32_e32 v6, v15, v19
	v_fma_f32 v10, v19, v15, -v6
	v_fmac_f32_e32 v10, v19, v16
	v_add_f32_e32 v18, v7, v2
	v_add_f32_e32 v2, v6, v10
	v_sub_f32_e32 v7, v3, v2
	v_pk_add_f32 v[12:13], v[2:3], v[6:7] neg_lo:[0,1] neg_hi:[0,1]
	v_mov_b32_e32 v11, v2
	v_pk_add_f32 v[2:3], v[12:13], v[10:11] neg_lo:[0,1] neg_hi:[0,1]
	s_mov_b32 s6, 0x3f317218
	v_add_f32_e32 v3, v18, v3
	v_add_f32_e32 v2, v2, v3
	v_add_f32_e32 v3, v7, v2
	v_mul_f32_e32 v18, v17, v3
	v_mul_f32_e32 v6, v15, v18
	v_fma_f32 v10, v18, v15, -v6
	v_fmac_f32_e32 v10, v18, v16
	v_sub_f32_e32 v7, v7, v3
	v_add_f32_e32 v15, v2, v7
	v_add_f32_e32 v2, v6, v10
	v_sub_f32_e32 v7, v3, v2
	v_pk_add_f32 v[12:13], v[2:3], v[6:7] neg_lo:[0,1] neg_hi:[0,1]
	v_mov_b32_e32 v11, v2
	v_pk_add_f32 v[2:3], v[12:13], v[10:11] neg_lo:[0,1] neg_hi:[0,1]
	s_nop 0
	v_add_f32_e32 v3, v15, v3
	v_add_f32_e32 v2, v2, v3
	v_add_f32_e32 v3, v19, v18
	v_add_f32_e32 v2, v7, v2
	v_sub_f32_e32 v6, v3, v19
	v_mul_f32_e32 v2, v17, v2
	v_sub_f32_e32 v6, v18, v6
	v_add_f32_e32 v6, v6, v2
	v_add_f32_e32 v10, v3, v6
	v_mul_f32_e32 v11, v10, v10
	v_fmamk_f32 v2, v11, 0x3e9b6dac, v229
	v_fmaak_f32 v199, v11, v2, 0x3f2aaada
	v_cvt_f32_i32_e32 v2, v14
	v_sub_f32_e32 v3, v10, v3
	v_sub_f32_e32 v3, v6, v3
	v_ldexp_f32 v12, v3, 1
	v_mul_f32_e32 v3, v10, v11
	v_ldexp_f32 v7, v10, 1
	v_pk_mul_f32 v[10:11], v[2:3], v[198:199]
	s_nop 0
	v_fma_f32 v6, v2, s6, -v10
	v_fmac_f32_e32 v6, 0xb102e308, v2
	v_pk_add_f32 v[2:3], v[10:11], v[6:7]
	s_mov_b32 s6, 0x7f800000
	v_sub_f32_e32 v7, v3, v7
	v_sub_f32_e32 v7, v11, v7
	v_add_f32_e32 v13, v12, v7
	v_mov_b32_e32 v12, v10
	v_pk_add_f32 v[10:11], v[2:3], v[10:11] neg_lo:[0,1] neg_hi:[0,1]
	v_pk_add_f32 v[14:15], v[2:3], v[12:13]
	v_mov_b32_e32 v7, v2
	v_mov_b32_e32 v11, v15
	v_pk_add_f32 v[16:17], v[6:7], v[10:11] neg_lo:[0,1] neg_hi:[0,1]
	v_pk_add_f32 v[6:7], v[6:7], v[10:11]
	v_mov_b32_e32 v12, v13
	v_pk_add_f32 v[10:11], v[6:7], v[2:3] op_sel:[1,0] op_sel_hi:[0,1] neg_lo:[0,1] neg_hi:[0,1]
	v_pk_add_f32 v[18:19], v[14:15], v[10:11] op_sel_hi:[1,0] neg_lo:[0,1] neg_hi:[0,1]
	v_mov_b32_e32 v14, v15
	v_mov_b32_e32 v15, v7
	v_pk_mov_b32 v[10:11], v[2:3], v[10:11] op_sel:[1,0]
	v_mov_b32_e32 v13, v2
	v_pk_add_f32 v[10:11], v[14:15], v[10:11] neg_lo:[0,1] neg_hi:[0,1]
	v_mov_b32_e32 v18, v16
	v_pk_add_f32 v[2:3], v[12:13], v[10:11] neg_lo:[0,1] neg_hi:[0,1]
	v_mov_b32_e32 v17, v7
	v_pk_add_f32 v[10:11], v[18:19], v[2:3]
	v_cmp_neq_f32_e32 vcc, s6, v20
	v_pk_add_f32 v[12:13], v[10:11], v[10:11] op_sel:[0,1] op_sel_hi:[1,0]
	s_mov_b32 s6, 0x33800000
	v_pk_add_f32 v[6:7], v[6:7], v[12:13] op_sel:[1,0] op_sel_hi:[0,1]
	v_mov_b32_e32 v11, v6
	v_pk_add_f32 v[14:15], v[10:11], v[16:17] neg_lo:[0,1] neg_hi:[0,1]
	v_mov_b32_e32 v3, v12
	v_sub_f32_e32 v7, v10, v14
	v_pk_add_f32 v[2:3], v[2:3], v[14:15] neg_lo:[0,1] neg_hi:[0,1]
	v_sub_f32_e32 v7, v16, v7
	v_add_f32_e32 v2, v2, v7
	v_add_f32_e32 v2, v2, v3
	v_add_f32_e32 v2, v6, v2
	v_cndmask_b32_e32 v2, v233, v2, vcc
	v_cmp_lt_f32_e64 vcc, |v20|, s6
	s_nop 1
	v_cndmask_b32_e32 v2, v2, v20, vcc
	v_add_f32_e32 v2, v9, v2
	v_mul_f32_e32 v2, v2, v194
	v_mul_f32_e32 v2, 0xbfb8aa3b, v2
	v_exp_f32_e32 v2, v2
	s_nop 0
	v_mul_f32_e32 v3, v5, v2
	ds_write_b128 v8, v[2:5] offset:1408
	s_branch .LBB0_332

; #define LAS __attribute__((address_space(3)))
; __device__ __forceinline__ void gd_task(const Params& p, LAS unsigned char* shm, const int tid, const int s, const int d, const int h, const int rq) {
;     ...
;                 for (int st = 0; st < TT; ++st) {
;                     const LAS float* sb = ib + st * GD_STRIDE;
;                     f32x2 kk[8], qq[8];
; #pragma unroll
;                     for (int e = 0; e < 4; ++e) { const f32x4 a = *(const LAS f32x4*)(sb + 20 * j + 4 * e), b = *(const LAS f32x4*)(sb + 160 + 20 * j + 4 * e);
;                         kk[2 * e] = (f32x2){a[0], a[1]}; kk[2 * e + 1] = (f32x2){a[2], a[3]}; qq[2 * e] = (f32x2){b[0], b[1]}; qq[2 * e + 1] = (f32x2){b[2], b[3]}; }
;                     const float v = sb[320 + row]; const f32x4 sc = *(const LAS f32x4*)(sb + 352); const float wdec = sc[0], cc = sc[1], kq = sc[2], beta = sc[3];
;                     f32x2 pa = sv[0] * kk[0], px = sv[0] * qq[0], pa2 = sv[1] * kk[1], px2 = sv[1] * qq[1];
; #pragma unroll
;                     for (int e = 2; e < 8; e += 2) { pa += sv[e] * kk[e]; px += sv[e] * qq[e]; pa2 += sv[e + 1] * kk[e + 1]; px2 += sv[e + 1] * qq[e + 1]; }
;                     pa += pa2; px += px2;
;                     const float sa = red8(pa[0] + pa[1]), x = red8(px[0] + px[1]);
;                     const float coef = beta * v - cc * sa; const float o = wdec * x + coef * kq;
;                     const f32x2 wd2 = (f32x2){wdec, wdec}, cf2 = (f32x2){coef, coef};
; #pragma unroll
;                     for (int e = 0; e < 8; ++e) sv[e] = sv[e] * wd2 + cf2 * kk[e];
;                     ow0[(st * 32) & omask] = o;
.Lgd_step:
	ds_read_b128 v[74:77], v130 offset:1424
	ds_read_b128 v[78:81], v130 offset:1440
	ds_read_b128 v[82:85], v130 offset:1456
	ds_read_b128 v[86:89], v130 offset:1472
	ds_read_b128 v[92:95], v130 offset:2064
	ds_read_b128 v[96:99], v130 offset:2080
	ds_read_b128 v[100:103], v130 offset:2096
	ds_read_b128 v[104:107], v130 offset:2112
	ds_read_b32 v112, v132 offset:1424
	ds_read_b128 v[108:111], v133 offset:2832
	s_waitcnt lgkmcnt(10)
	v_pk_mul_f32 v[64:65], v[2:3], v[26:27]
	v_pk_mul_f32 v[68:69], v[2:3], v[42:43]
	v_pk_fma_f32 v[64:65], v[4:5], v[28:29], v[64:65]
	v_pk_fma_f32 v[68:69], v[4:5], v[44:45], v[68:69]
	v_pk_fma_f32 v[64:65], v[6:7], v[30:31], v[64:65]
	v_pk_fma_f32 v[68:69], v[6:7], v[46:47], v[68:69]
	v_pk_fma_f32 v[64:65], v[8:9], v[32:33], v[64:65]
	v_pk_fma_f32 v[68:69], v[8:9], v[48:49], v[68:69]
	v_pk_fma_f32 v[64:65], v[10:11], v[34:35], v[64:65]
	v_pk_fma_f32 v[68:69], v[10:11], v[50:51], v[68:69]
	v_pk_fma_f32 v[64:65], v[12:13], v[36:37], v[64:65]
	v_pk_fma_f32 v[68:69], v[12:13], v[52:53], v[68:69]
	v_pk_fma_f32 v[64:65], v[14:15], v[38:39], v[64:65]
	v_pk_fma_f32 v[68:69], v[14:15], v[54:55], v[68:69]
	v_pk_fma_f32 v[64:65], v[16:17], v[40:41], v[64:65]
	v_pk_fma_f32 v[68:69], v[16:17], v[56:57], v[68:69]
	v_pk_mul_f32 v[114:115], v[2:3], v[58:59] op_sel_hi:[1,0]
	v_add_f32_e32 v63, v64, v65
	v_add_f32_e32 v72, v68, v69
	v_pk_mul_f32 v[116:117], v[4:5], v[58:59] op_sel_hi:[1,0]
	v_pk_mul_f32 v[118:119], v[6:7], v[58:59] op_sel_hi:[1,0]
	v_add_f32_dpp v63, v63, v63 quad_perm:[1,0,3,2] row_mask:0xf bank_mask:0xf bound_ctrl:1
	v_add_f32_dpp v72, v72, v72 quad_perm:[1,0,3,2] row_mask:0xf bank_mask:0xf bound_ctrl:1
	v_pk_mul_f32 v[120:121], v[8:9], v[58:59] op_sel_hi:[1,0]
	v_add_f32_dpp v63, v63, v63 quad_perm:[2,3,0,1] row_mask:0xf bank_mask:0xf bound_ctrl:1
	v_add_f32_dpp v72, v72, v72 quad_perm:[2,3,0,1] row_mask:0xf bank_mask:0xf bound_ctrl:1
	v_pk_mul_f32 v[122:123], v[10:11], v[58:59] op_sel_hi:[1,0]
	v_add_f32_dpp v63, v63, v63 row_half_mirror row_mask:0xf bank_mask:0xf bound_ctrl:1
	v_add_f32_dpp v72, v72, v72 row_half_mirror row_mask:0xf bank_mask:0xf bound_ctrl:1
	v_pk_mul_f32 v[124:125], v[12:13], v[58:59] op_sel_hi:[1,0]
	v_mul_f32_e32 v73, v63, v59
	v_pk_mul_f32 v[126:127], v[14:15], v[58:59] op_sel_hi:[1,0]
	v_fma_f32 v138, v62, v61, -v73
	v_pk_mul_f32 v[128:129], v[16:17], v[58:59] op_sel_hi:[1,0]
	v_pk_fma_f32 v[2:3], v[26:27], v[138:139], v[114:115] op_sel_hi:[1,0,1]
	v_mul_f32_e32 v113, v138, v60
	v_pk_fma_f32 v[4:5], v[28:29], v[138:139], v[116:117] op_sel_hi:[1,0,1]
	v_pk_fma_f32 v[6:7], v[30:31], v[138:139], v[118:119] op_sel_hi:[1,0,1]
	v_fma_f32 v137, v58, v72, v113
	v_pk_fma_f32 v[8:9], v[32:33], v[138:139], v[120:121] op_sel_hi:[1,0,1]
	v_pk_fma_f32 v[10:11], v[34:35], v[138:139], v[122:123] op_sel_hi:[1,0,1]
	ds_write_b32 v136, v137 offset:0
	v_pk_fma_f32 v[12:13], v[36:37], v[138:139], v[124:125] op_sel_hi:[1,0,1]
	v_pk_fma_f32 v[14:15], v[38:39], v[138:139], v[126:127] op_sel_hi:[1,0,1]
	v_pk_fma_f32 v[16:17], v[40:41], v[138:139], v[128:129] op_sel_hi:[1,0,1]
	ds_read_b128 v[26:29], v130 offset:2848
	ds_read_b128 v[30:33], v130 offset:2864
	ds_read_b128 v[34:37], v130 offset:2880
	ds_read_b128 v[38:41], v130 offset:2896
	ds_read_b128 v[42:45], v130 offset:3488
	ds_read_b128 v[46:49], v130 offset:3504
	ds_read_b128 v[50:53], v130 offset:3520
	ds_read_b128 v[54:57], v130 offset:3536
	ds_read_b32 v62, v132 offset:2848
	ds_read_b128 v[58:61], v133 offset:4256
	s_waitcnt lgkmcnt(10)
	v_pk_mul_f32 v[64:65], v[2:3], v[74:75]
	v_pk_mul_f32 v[68:69], v[2:3], v[92:93]
	v_pk_fma_f32 v[64:65], v[4:5], v[76:77], v[64:65]
	v_pk_fma_f32 v[68:69], v[4:5], v[94:95], v[68:69]
	v_pk_fma_f32 v[64:65], v[6:7], v[78:79], v[64:65]
	v_pk_fma_f32 v[68:69], v[6:7], v[96:97], v[68:69]
	v_pk_fma_f32 v[64:65], v[8:9], v[80:81], v[64:65]
	v_pk_fma_f32 v[68:69], v[8:9], v[98:99], v[68:69]
	v_pk_fma_f32 v[64:65], v[10:11], v[82:83], v[64:65]
	v_pk_fma_f32 v[68:69], v[10:11], v[100:101], v[68:69]
	v_pk_fma_f32 v[64:65], v[12:13], v[84:85], v[64:65]
	v_pk_fma_f32 v[68:69], v[12:13], v[102:103], v[68:69]
	v_pk_fma_f32 v[64:65], v[14:15], v[86:87], v[64:65]
	v_pk_fma_f32 v[68:69], v[14:15], v[104:105], v[68:69]
	v_pk_fma_f32 v[64:65], v[16:17], v[88:89], v[64:65]
	v_pk_fma_f32 v[68:69], v[16:17], v[106:107], v[68:69]
	v_pk_mul_f32 v[114:115], v[2:3], v[108:109] op_sel_hi:[1,0]
	v_add_f32_e32 v63, v64, v65
	v_add_f32_e32 v72, v68, v69
	v_pk_mul_f32 v[116:117], v[4:5], v[108:109] op_sel_hi:[1,0]
	v_pk_mul_f32 v[118:119], v[6:7], v[108:109] op_sel_hi:[1,0]
	v_add_f32_dpp v63, v63, v63 quad_perm:[1,0,3,2] row_mask:0xf bank_mask:0xf bound_ctrl:1
	v_add_f32_dpp v72, v72, v72 quad_perm:[1,0,3,2] row_mask:0xf bank_mask:0xf bound_ctrl:1
	v_pk_mul_f32 v[120:121], v[8:9], v[108:109] op_sel_hi:[1,0]
	v_add_f32_dpp v63, v63, v63 quad_perm:[2,3,0,1] row_mask:0xf bank_mask:0xf bound_ctrl:1
	v_add_f32_dpp v72, v72, v72 quad_perm:[2,3,0,1] row_mask:0xf bank_mask:0xf bound_ctrl:1
	v_pk_mul_f32 v[122:123], v[10:11], v[108:109] op_sel_hi:[1,0]
	v_add_f32_dpp v63, v63, v63 row_half_mirror row_mask:0xf bank_mask:0xf bound_ctrl:1
	v_add_f32_dpp v72, v72, v72 row_half_mirror row_mask:0xf bank_mask:0xf bound_ctrl:1
	v_pk_mul_f32 v[124:125], v[12:13], v[108:109] op_sel_hi:[1,0]
	v_mul_f32_e32 v73, v63, v109
	v_pk_mul_f32 v[126:127], v[14:15], v[108:109] op_sel_hi:[1,0]
	v_fma_f32 v138, v112, v111, -v73
	v_pk_mul_f32 v[128:129], v[16:17], v[108:109] op_sel_hi:[1,0]
	v_pk_fma_f32 v[2:3], v[74:75], v[138:139], v[114:115] op_sel_hi:[1,0,1]
	v_mul_f32_e32 v113, v138, v110
	v_pk_fma_f32 v[4:5], v[76:77], v[138:139], v[116:117] op_sel_hi:[1,0,1]
	v_pk_fma_f32 v[6:7], v[78:79], v[138:139], v[118:119] op_sel_hi:[1,0,1]
	v_fma_f32 v137, v108, v72, v113
	v_pk_fma_f32 v[8:9], v[80:81], v[138:139], v[120:121] op_sel_hi:[1,0,1]
	v_pk_fma_f32 v[10:11], v[82:83], v[138:139], v[122:123] op_sel_hi:[1,0,1]
	ds_write_b32 v136, v137 offset:128
	v_pk_fma_f32 v[12:13], v[84:85], v[138:139], v[124:125] op_sel_hi:[1,0,1]
	v_pk_fma_f32 v[14:15], v[86:87], v[138:139], v[126:127] op_sel_hi:[1,0,1]
	v_pk_fma_f32 v[16:17], v[88:89], v[138:139], v[128:129] op_sel_hi:[1,0,1]
	ds_read_b128 v[74:77], v130 offset:4272
	ds_read_b128 v[78:81], v130 offset:4288
	ds_read_b128 v[82:85], v130 offset:4304
	ds_read_b128 v[86:89], v130 offset:4320
	ds_read_b128 v[92:95], v130 offset:4912
	ds_read_b128 v[96:99], v130 offset:4928
	ds_read_b128 v[100:103], v130 offset:4944
	ds_read_b128 v[104:107], v130 offset:4960
	ds_read_b32 v112, v132 offset:4272
	ds_read_b128 v[108:111], v133 offset:5680
	s_waitcnt lgkmcnt(10)
; #define LAS __attribute__((address_space(3)))
; __device__ __forceinline__ void gd_task(const Params& p, LAS unsigned char* shm, const int tid, const int s, const int d, const int h, const int rq) {
;     ...
;                 for (int st = 0; st < TT; ++st) {
;                     const LAS float* sb = ib + st * GD_STRIDE;
;                     f32x2 kk[8], qq[8];
; #pragma unroll
;                     for (int e = 0; e < 4; ++e) { const f32x4 a = *(const LAS f32x4*)(sb + 20 * j + 4 * e), b = *(const LAS f32x4*)(sb + 160 + 20 * j + 4 * e);
;                         kk[2 * e] = (f32x2){a[0], a[1]}; kk[2 * e + 1] = (f32x2){a[2], a[3]}; qq[2 * e] = (f32x2){b[0], b[1]}; qq[2 * e + 1] = (f32x2){b[2], b[3]}; }
;                     const float v = sb[320 + row]; const f32x4 sc = *(const LAS f32x4*)(sb + 352); const float wdec = sc[0], cc = sc[1], kq = sc[2], beta = sc[3];
;                     f32x2 pa = sv[0] * kk[0], px = sv[0] * qq[0], pa2 = sv[1] * kk[1], px2 = sv[1] * qq[1];
; #pragma unroll
;                     for (int e = 2; e < 8; e += 2) { pa += sv[e] * kk[e]; px += sv[e] * qq[e]; pa2 += sv[e + 1] * kk[e + 1]; px2 += sv[e + 1] * qq[e + 1]; }
;                     pa += pa2; px += px2;
;                     const float sa = red8(pa[0] + pa[1]), x = red8(px[0] + px[1]);
;                     const float coef = beta * v - cc * sa; const float o = wdec * x + coef * kq;
;                     const f32x2 wd2 = (f32x2){wdec, wdec}, cf2 = (f32x2){coef, coef};
; #pragma unroll
;                     for (int e = 0; e < 8; ++e) sv[e] = sv[e] * wd2 + cf2 * kk[e];
;                     ow0[(st * 32) & omask] = o;
	v_pk_mul_f32 v[64:65], v[2:3], v[26:27]
	v_pk_mul_f32 v[68:69], v[2:3], v[42:43]
	v_pk_fma_f32 v[64:65], v[4:5], v[28:29], v[64:65]
	v_pk_fma_f32 v[68:69], v[4:5], v[44:45], v[68:69]
	v_pk_fma_f32 v[64:65], v[6:7], v[30:31], v[64:65]
	v_pk_fma_f32 v[68:69], v[6:7], v[46:47], v[68:69]
	v_pk_fma_f32 v[64:65], v[8:9], v[32:33], v[64:65]
	v_pk_fma_f32 v[68:69], v[8:9], v[48:49], v[68:69]
	v_pk_fma_f32 v[64:65], v[10:11], v[34:35], v[64:65]
	v_pk_fma_f32 v[68:69], v[10:11], v[50:51], v[68:69]
	v_pk_fma_f32 v[64:65], v[12:13], v[36:37], v[64:65]
	v_pk_fma_f32 v[68:69], v[12:13], v[52:53], v[68:69]
	v_pk_fma_f32 v[64:65], v[14:15], v[38:39], v[64:65]
	v_pk_fma_f32 v[68:69], v[14:15], v[54:55], v[68:69]
	v_pk_fma_f32 v[64:65], v[16:17], v[40:41], v[64:65]
	v_pk_fma_f32 v[68:69], v[16:17], v[56:57], v[68:69]
	v_pk_mul_f32 v[114:115], v[2:3], v[58:59] op_sel_hi:[1,0]
	v_add_f32_e32 v63, v64, v65
	v_add_f32_e32 v72, v68, v69
	v_pk_mul_f32 v[116:117], v[4:5], v[58:59] op_sel_hi:[1,0]
	v_pk_mul_f32 v[118:119], v[6:7], v[58:59] op_sel_hi:[1,0]
	v_add_f32_dpp v63, v63, v63 quad_perm:[1,0,3,2] row_mask:0xf bank_mask:0xf bound_ctrl:1
	v_add_f32_dpp v72, v72, v72 quad_perm:[1,0,3,2] row_mask:0xf bank_mask:0xf bound_ctrl:1
	v_pk_mul_f32 v[120:121], v[8:9], v[58:59] op_sel_hi:[1,0]
	v_add_f32_dpp v63, v63, v63 quad_perm:[2,3,0,1] row_mask:0xf bank_mask:0xf bound_ctrl:1
	v_add_f32_dpp v72, v72, v72 quad_perm:[2,3,0,1] row_mask:0xf bank_mask:0xf bound_ctrl:1
	v_pk_mul_f32 v[122:123], v[10:11], v[58:59] op_sel_hi:[1,0]
	v_add_f32_dpp v63, v63, v63 row_half_mirror row_mask:0xf bank_mask:0xf bound_ctrl:1
	v_add_f32_dpp v72, v72, v72 row_half_mirror row_mask:0xf bank_mask:0xf bound_ctrl:1
	v_pk_mul_f32 v[124:125], v[12:13], v[58:59] op_sel_hi:[1,0]
	v_mul_f32_e32 v73, v63, v59
	v_pk_mul_f32 v[126:127], v[14:15], v[58:59] op_sel_hi:[1,0]
	v_fma_f32 v138, v62, v61, -v73
	v_pk_mul_f32 v[128:129], v[16:17], v[58:59] op_sel_hi:[1,0]
	v_pk_fma_f32 v[2:3], v[26:27], v[138:139], v[114:115] op_sel_hi:[1,0,1]
	v_mul_f32_e32 v113, v138, v60
	v_pk_fma_f32 v[4:5], v[28:29], v[138:139], v[116:117] op_sel_hi:[1,0,1]
	v_pk_fma_f32 v[6:7], v[30:31], v[138:139], v[118:119] op_sel_hi:[1,0,1]
	v_fma_f32 v137, v58, v72, v113
	v_pk_fma_f32 v[8:9], v[32:33], v[138:139], v[120:121] op_sel_hi:[1,0,1]
	v_pk_fma_f32 v[10:11], v[34:35], v[138:139], v[122:123] op_sel_hi:[1,0,1]
	ds_write_b32 v136, v137 offset:256
	v_pk_fma_f32 v[12:13], v[36:37], v[138:139], v[124:125] op_sel_hi:[1,0,1]
	v_pk_fma_f32 v[14:15], v[38:39], v[138:139], v[126:127] op_sel_hi:[1,0,1]
	v_pk_fma_f32 v[16:17], v[40:41], v[138:139], v[128:129] op_sel_hi:[1,0,1]
	ds_read_b128 v[26:29], v130 offset:5696
	ds_read_b128 v[30:33], v130 offset:5712
	ds_read_b128 v[34:37], v130 offset:5728
	ds_read_b128 v[38:41], v130 offset:5744
	ds_read_b128 v[42:45], v130 offset:6336
	ds_read_b128 v[46:49], v130 offset:6352
	ds_read_b128 v[50:53], v130 offset:6368
	ds_read_b128 v[54:57], v130 offset:6384
	ds_read_b32 v62, v132 offset:5696
	ds_read_b128 v[58:61], v133 offset:7104
	s_waitcnt lgkmcnt(10)
	v_pk_mul_f32 v[64:65], v[2:3], v[74:75]
	v_pk_mul_f32 v[68:69], v[2:3], v[92:93]
	v_pk_fma_f32 v[64:65], v[4:5], v[76:77], v[64:65]
	v_pk_fma_f32 v[68:69], v[4:5], v[94:95], v[68:69]
	v_pk_fma_f32 v[64:65], v[6:7], v[78:79], v[64:65]
	v_pk_fma_f32 v[68:69], v[6:7], v[96:97], v[68:69]
	v_pk_fma_f32 v[64:65], v[8:9], v[80:81], v[64:65]
	v_pk_fma_f32 v[68:69], v[8:9], v[98:99], v[68:69]
	v_pk_fma_f32 v[64:65], v[10:11], v[82:83], v[64:65]
	v_pk_fma_f32 v[68:69], v[10:11], v[100:101], v[68:69]
	v_pk_fma_f32 v[64:65], v[12:13], v[84:85], v[64:65]
	v_pk_fma_f32 v[68:69], v[12:13], v[102:103], v[68:69]
	v_pk_fma_f32 v[64:65], v[14:15], v[86:87], v[64:65]
	v_pk_fma_f32 v[68:69], v[14:15], v[104:105], v[68:69]
	v_pk_fma_f32 v[64:65], v[16:17], v[88:89], v[64:65]
	v_pk_fma_f32 v[68:69], v[16:17], v[106:107], v[68:69]
	v_pk_mul_f32 v[114:115], v[2:3], v[108:109] op_sel_hi:[1,0]
	v_add_f32_e32 v63, v64, v65
	v_add_f32_e32 v72, v68, v69
	v_pk_mul_f32 v[116:117], v[4:5], v[108:109] op_sel_hi:[1,0]
	v_pk_mul_f32 v[118:119], v[6:7], v[108:109] op_sel_hi:[1,0]
	v_add_f32_dpp v63, v63, v63 quad_perm:[1,0,3,2] row_mask:0xf bank_mask:0xf bound_ctrl:1
	v_add_f32_dpp v72, v72, v72 quad_perm:[1,0,3,2] row_mask:0xf bank_mask:0xf bound_ctrl:1
	v_pk_mul_f32 v[120:121], v[8:9], v[108:109] op_sel_hi:[1,0]
	v_add_f32_dpp v63, v63, v63 quad_perm:[2,3,0,1] row_mask:0xf bank_mask:0xf bound_ctrl:1
	v_add_f32_dpp v72, v72, v72 quad_perm:[2,3,0,1] row_mask:0xf bank_mask:0xf bound_ctrl:1
	v_pk_mul_f32 v[122:123], v[10:11], v[108:109] op_sel_hi:[1,0]
	v_add_f32_dpp v63, v63, v63 row_half_mirror row_mask:0xf bank_mask:0xf bound_ctrl:1
	v_add_f32_dpp v72, v72, v72 row_half_mirror row_mask:0xf bank_mask:0xf bound_ctrl:1
	v_pk_mul_f32 v[124:125], v[12:13], v[108:109] op_sel_hi:[1,0]
	v_mul_f32_e32 v73, v63, v109
	v_pk_mul_f32 v[126:127], v[14:15], v[108:109] op_sel_hi:[1,0]
	v_fma_f32 v138, v112, v111, -v73
	v_pk_mul_f32 v[128:129], v[16:17], v[108:109] op_sel_hi:[1,0]
	v_pk_fma_f32 v[2:3], v[74:75], v[138:139], v[114:115] op_sel_hi:[1,0,1]
	v_mul_f32_e32 v113, v138, v110
	v_pk_fma_f32 v[4:5], v[76:77], v[138:139], v[116:117] op_sel_hi:[1,0,1]
	v_pk_fma_f32 v[6:7], v[78:79], v[138:139], v[118:119] op_sel_hi:[1,0,1]
	v_fma_f32 v137, v108, v72, v113
	v_pk_fma_f32 v[8:9], v[80:81], v[138:139], v[120:121] op_sel_hi:[1,0,1]
	v_pk_fma_f32 v[10:11], v[82:83], v[138:139], v[122:123] op_sel_hi:[1,0,1]
	ds_write_b32 v136, v137 offset:384
	v_pk_fma_f32 v[12:13], v[84:85], v[138:139], v[124:125] op_sel_hi:[1,0,1]
	v_pk_fma_f32 v[14:15], v[86:87], v[138:139], v[126:127] op_sel_hi:[1,0,1]
	v_pk_fma_f32 v[16:17], v[88:89], v[138:139], v[128:129] op_sel_hi:[1,0,1]
	ds_read_b128 v[74:77], v130 offset:7120
	ds_read_b128 v[78:81], v130 offset:7136
	ds_read_b128 v[82:85], v130 offset:7152
	ds_read_b128 v[86:89], v130 offset:7168
	ds_read_b128 v[92:95], v130 offset:7760
	ds_read_b128 v[96:99], v130 offset:7776
	ds_read_b128 v[100:103], v130 offset:7792
	ds_read_b128 v[104:107], v130 offset:7808
	ds_read_b32 v112, v132 offset:7120
	ds_read_b128 v[108:111], v133 offset:8528
	s_waitcnt lgkmcnt(10)
; #define LAS __attribute__((address_space(3)))
; __device__ __forceinline__ void gd_task(const Params& p, LAS unsigned char* shm, const int tid, const int s, const int d, const int h, const int rq) {
;     ...
;                 for (int st = 0; st < TT; ++st) {
;                     const LAS float* sb = ib + st * GD_STRIDE;
;                     f32x2 kk[8], qq[8];
; #pragma unroll
;                     for (int e = 0; e < 4; ++e) { const f32x4 a = *(const LAS f32x4*)(sb + 20 * j + 4 * e), b = *(const LAS f32x4*)(sb + 160 + 20 * j + 4 * e);
;                         kk[2 * e] = (f32x2){a[0], a[1]}; kk[2 * e + 1] = (f32x2){a[2], a[3]}; qq[2 * e] = (f32x2){b[0], b[1]}; qq[2 * e + 1] = (f32x2){b[2], b[3]}; }
;                     const float v = sb[320 + row]; const f32x4 sc = *(const LAS f32x4*)(sb + 352); const float wdec = sc[0], cc = sc[1], kq = sc[2], beta = sc[3];
;                     f32x2 pa = sv[0] * kk[0], px = sv[0] * qq[0], pa2 = sv[1] * kk[1], px2 = sv[1] * qq[1];
; #pragma unroll
;                     for (int e = 2; e < 8; e += 2) { pa += sv[e] * kk[e]; px += sv[e] * qq[e]; pa2 += sv[e + 1] * kk[e + 1]; px2 += sv[e + 1] * qq[e + 1]; }
;                     pa += pa2; px += px2;
;                     const float sa = red8(pa[0] + pa[1]), x = red8(px[0] + px[1]);
;                     const float coef = beta * v - cc * sa; const float o = wdec * x + coef * kq;
;                     const f32x2 wd2 = (f32x2){wdec, wdec}, cf2 = (f32x2){coef, coef};
; #pragma unroll
;                     for (int e = 0; e < 8; ++e) sv[e] = sv[e] * wd2 + cf2 * kk[e];
;                     ow0[(st * 32) & omask] = o;
	v_pk_mul_f32 v[64:65], v[2:3], v[26:27]
	v_pk_mul_f32 v[68:69], v[2:3], v[42:43]
	v_pk_fma_f32 v[64:65], v[4:5], v[28:29], v[64:65]
	v_pk_fma_f32 v[68:69], v[4:5], v[44:45], v[68:69]
	v_pk_fma_f32 v[64:65], v[6:7], v[30:31], v[64:65]
	v_pk_fma_f32 v[68:69], v[6:7], v[46:47], v[68:69]
	v_pk_fma_f32 v[64:65], v[8:9], v[32:33], v[64:65]
	v_pk_fma_f32 v[68:69], v[8:9], v[48:49], v[68:69]
	v_pk_fma_f32 v[64:65], v[10:11], v[34:35], v[64:65]
	v_pk_fma_f32 v[68:69], v[10:11], v[50:51], v[68:69]
	v_pk_fma_f32 v[64:65], v[12:13], v[36:37], v[64:65]
	v_pk_fma_f32 v[68:69], v[12:13], v[52:53], v[68:69]
	v_pk_fma_f32 v[64:65], v[14:15], v[38:39], v[64:65]
	v_pk_fma_f32 v[68:69], v[14:15], v[54:55], v[68:69]
	v_pk_fma_f32 v[64:65], v[16:17], v[40:41], v[64:65]
	v_pk_fma_f32 v[68:69], v[16:17], v[56:57], v[68:69]
	v_pk_mul_f32 v[114:115], v[2:3], v[58:59] op_sel_hi:[1,0]
	v_add_f32_e32 v63, v64, v65
	v_add_f32_e32 v72, v68, v69
	v_pk_mul_f32 v[116:117], v[4:5], v[58:59] op_sel_hi:[1,0]
	v_pk_mul_f32 v[118:119], v[6:7], v[58:59] op_sel_hi:[1,0]
	v_add_f32_dpp v63, v63, v63 quad_perm:[1,0,3,2] row_mask:0xf bank_mask:0xf bound_ctrl:1
	v_add_f32_dpp v72, v72, v72 quad_perm:[1,0,3,2] row_mask:0xf bank_mask:0xf bound_ctrl:1
	v_pk_mul_f32 v[120:121], v[8:9], v[58:59] op_sel_hi:[1,0]
	v_add_f32_dpp v63, v63, v63 quad_perm:[2,3,0,1] row_mask:0xf bank_mask:0xf bound_ctrl:1
	v_add_f32_dpp v72, v72, v72 quad_perm:[2,3,0,1] row_mask:0xf bank_mask:0xf bound_ctrl:1
	v_pk_mul_f32 v[122:123], v[10:11], v[58:59] op_sel_hi:[1,0]
	v_add_f32_dpp v63, v63, v63 row_half_mirror row_mask:0xf bank_mask:0xf bound_ctrl:1
	v_add_f32_dpp v72, v72, v72 row_half_mirror row_mask:0xf bank_mask:0xf bound_ctrl:1
	v_pk_mul_f32 v[124:125], v[12:13], v[58:59] op_sel_hi:[1,0]
	v_mul_f32_e32 v73, v63, v59
	v_pk_mul_f32 v[126:127], v[14:15], v[58:59] op_sel_hi:[1,0]
	v_fma_f32 v138, v62, v61, -v73
	v_pk_mul_f32 v[128:129], v[16:17], v[58:59] op_sel_hi:[1,0]
	v_pk_fma_f32 v[2:3], v[26:27], v[138:139], v[114:115] op_sel_hi:[1,0,1]
	v_mul_f32_e32 v113, v138, v60
	v_pk_fma_f32 v[4:5], v[28:29], v[138:139], v[116:117] op_sel_hi:[1,0,1]
	v_pk_fma_f32 v[6:7], v[30:31], v[138:139], v[118:119] op_sel_hi:[1,0,1]
	v_fma_f32 v137, v58, v72, v113
	v_pk_fma_f32 v[8:9], v[32:33], v[138:139], v[120:121] op_sel_hi:[1,0,1]
	v_pk_fma_f32 v[10:11], v[34:35], v[138:139], v[122:123] op_sel_hi:[1,0,1]
	ds_write_b32 v136, v137 offset:512
	v_pk_fma_f32 v[12:13], v[36:37], v[138:139], v[124:125] op_sel_hi:[1,0,1]
	v_pk_fma_f32 v[14:15], v[38:39], v[138:139], v[126:127] op_sel_hi:[1,0,1]
	v_pk_fma_f32 v[16:17], v[40:41], v[138:139], v[128:129] op_sel_hi:[1,0,1]
	ds_read_b128 v[26:29], v130 offset:8544
	ds_read_b128 v[30:33], v130 offset:8560
	ds_read_b128 v[34:37], v130 offset:8576
	ds_read_b128 v[38:41], v130 offset:8592
	ds_read_b128 v[42:45], v130 offset:9184
	ds_read_b128 v[46:49], v130 offset:9200
	ds_read_b128 v[50:53], v130 offset:9216
	ds_read_b128 v[54:57], v130 offset:9232
	ds_read_b32 v62, v132 offset:8544
	ds_read_b128 v[58:61], v133 offset:9952
	s_waitcnt lgkmcnt(10)
	v_pk_mul_f32 v[64:65], v[2:3], v[74:75]
	v_pk_mul_f32 v[68:69], v[2:3], v[92:93]
	v_pk_fma_f32 v[64:65], v[4:5], v[76:77], v[64:65]
	v_pk_fma_f32 v[68:69], v[4:5], v[94:95], v[68:69]
	v_pk_fma_f32 v[64:65], v[6:7], v[78:79], v[64:65]
	v_pk_fma_f32 v[68:69], v[6:7], v[96:97], v[68:69]
	v_pk_fma_f32 v[64:65], v[8:9], v[80:81], v[64:65]
	v_pk_fma_f32 v[68:69], v[8:9], v[98:99], v[68:69]
	v_pk_fma_f32 v[64:65], v[10:11], v[82:83], v[64:65]
	v_pk_fma_f32 v[68:69], v[10:11], v[100:101], v[68:69]
	v_pk_fma_f32 v[64:65], v[12:13], v[84:85], v[64:65]
	v_pk_fma_f32 v[68:69], v[12:13], v[102:103], v[68:69]
	v_pk_fma_f32 v[64:65], v[14:15], v[86:87], v[64:65]
	v_pk_fma_f32 v[68:69], v[14:15], v[104:105], v[68:69]
	v_pk_fma_f32 v[64:65], v[16:17], v[88:89], v[64:65]
	v_pk_fma_f32 v[68:69], v[16:17], v[106:107], v[68:69]
	v_pk_mul_f32 v[114:115], v[2:3], v[108:109] op_sel_hi:[1,0]
	v_add_f32_e32 v63, v64, v65
	v_add_f32_e32 v72, v68, v69
	v_pk_mul_f32 v[116:117], v[4:5], v[108:109] op_sel_hi:[1,0]
	v_pk_mul_f32 v[118:119], v[6:7], v[108:109] op_sel_hi:[1,0]
	v_add_f32_dpp v63, v63, v63 quad_perm:[1,0,3,2] row_mask:0xf bank_mask:0xf bound_ctrl:1
	v_add_f32_dpp v72, v72, v72 quad_perm:[1,0,3,2] row_mask:0xf bank_mask:0xf bound_ctrl:1
	v_pk_mul_f32 v[120:121], v[8:9], v[108:109] op_sel_hi:[1,0]
	v_add_f32_dpp v63, v63, v63 quad_perm:[2,3,0,1] row_mask:0xf bank_mask:0xf bound_ctrl:1
	v_add_f32_dpp v72, v72, v72 quad_perm:[2,3,0,1] row_mask:0xf bank_mask:0xf bound_ctrl:1
	v_pk_mul_f32 v[122:123], v[10:11], v[108:109] op_sel_hi:[1,0]
	v_add_f32_dpp v63, v63, v63 row_half_mirror row_mask:0xf bank_mask:0xf bound_ctrl:1
	v_add_f32_dpp v72, v72, v72 row_half_mirror row_mask:0xf bank_mask:0xf bound_ctrl:1
	v_pk_mul_f32 v[124:125], v[12:13], v[108:109] op_sel_hi:[1,0]
	v_mul_f32_e32 v73, v63, v109
	v_pk_mul_f32 v[126:127], v[14:15], v[108:109] op_sel_hi:[1,0]
	v_fma_f32 v138, v112, v111, -v73
	v_pk_mul_f32 v[128:129], v[16:17], v[108:109] op_sel_hi:[1,0]
	v_pk_fma_f32 v[2:3], v[74:75], v[138:139], v[114:115] op_sel_hi:[1,0,1]
	v_mul_f32_e32 v113, v138, v110
	v_pk_fma_f32 v[4:5], v[76:77], v[138:139], v[116:117] op_sel_hi:[1,0,1]
	v_pk_fma_f32 v[6:7], v[78:79], v[138:139], v[118:119] op_sel_hi:[1,0,1]
	v_fma_f32 v137, v108, v72, v113
	v_pk_fma_f32 v[8:9], v[80:81], v[138:139], v[120:121] op_sel_hi:[1,0,1]
	v_pk_fma_f32 v[10:11], v[82:83], v[138:139], v[122:123] op_sel_hi:[1,0,1]
	ds_write_b32 v136, v137 offset:640
	v_pk_fma_f32 v[12:13], v[84:85], v[138:139], v[124:125] op_sel_hi:[1,0,1]
	v_pk_fma_f32 v[14:15], v[86:87], v[138:139], v[126:127] op_sel_hi:[1,0,1]
	v_pk_fma_f32 v[16:17], v[88:89], v[138:139], v[128:129] op_sel_hi:[1,0,1]
	ds_read_b128 v[74:77], v130 offset:9968
	ds_read_b128 v[78:81], v130 offset:9984
	ds_read_b128 v[82:85], v130 offset:10000
	ds_read_b128 v[86:89], v130 offset:10016
	ds_read_b128 v[92:95], v130 offset:10608
	ds_read_b128 v[96:99], v130 offset:10624
	ds_read_b128 v[100:103], v130 offset:10640
	ds_read_b128 v[104:107], v130 offset:10656
	ds_read_b32 v112, v132 offset:9968
	ds_read_b128 v[108:111], v133 offset:11376
	s_waitcnt lgkmcnt(10)
; #define LAS __attribute__((address_space(3)))
; __device__ __forceinline__ void gd_task(const Params& p, LAS unsigned char* shm, const int tid, const int s, const int d, const int h, const int rq) {
;     ...
;             for (int ti = 0; ti < ntiles; ++ti) {
;                 const LAS float* ib = inb + (ti & 1) * GD_INF; LAS float* ob = outb + (ti & 1) * GD_OUTF;
;                 LAS float* ow0 = j == 0 ? ob + row : outb + 2 * GD_OUTF + l; const int omask = j == 0 ? -1 : 0;
; #pragma unroll 2
;                 for (int st = 0; st < TT; ++st) {
;                     const LAS float* sb = ib + st * GD_STRIDE;
;                     f32x2 kk[8], qq[8];
; #pragma unroll
;                     for (int e = 0; e < 4; ++e) { const f32x4 a = *(const LAS f32x4*)(sb + 20 * j + 4 * e), b = *(const LAS f32x4*)(sb + 160 + 20 * j + 4 * e);
;                         kk[2 * e] = (f32x2){a[0], a[1]}; kk[2 * e + 1] = (f32x2){a[2], a[3]}; qq[2 * e] = (f32x2){b[0], b[1]}; qq[2 * e + 1] = (f32x2){b[2], b[3]}; }
;                     const float v = sb[320 + row]; const f32x4 sc = *(const LAS f32x4*)(sb + 352); const float wdec = sc[0], cc = sc[1], kq = sc[2], beta = sc[3];
;                     f32x2 pa = sv[0] * kk[0], px = sv[0] * qq[0], pa2 = sv[1] * kk[1], px2 = sv[1] * qq[1];
; #pragma unroll
;                     for (int e = 2; e < 8; e += 2) { pa += sv[e] * kk[e]; px += sv[e] * qq[e]; pa2 += sv[e + 1] * kk[e + 1]; px2 += sv[e + 1] * qq[e + 1]; }
;                     pa += pa2; px += px2;
;                     const float sa = red8(pa[0] + pa[1]), x = red8(px[0] + px[1]);
;                     const float coef = beta * v - cc * sa; const float o = wdec * x + coef * kq;
;                     const f32x2 wd2 = (f32x2){wdec, wdec}, cf2 = (f32x2){coef, coef};
; #pragma unroll
;                     for (int e = 0; e < 8; ++e) sv[e] = sv[e] * wd2 + cf2 * kk[e];
;                     ow0[(st * 32) & omask] = o;
;                 }
;                 __syncthreads();
;             }
	v_pk_mul_f32 v[64:65], v[2:3], v[26:27]
	v_pk_mul_f32 v[68:69], v[2:3], v[42:43]
	v_pk_fma_f32 v[64:65], v[4:5], v[28:29], v[64:65]
	v_pk_fma_f32 v[68:69], v[4:5], v[44:45], v[68:69]
	v_pk_fma_f32 v[64:65], v[6:7], v[30:31], v[64:65]
	v_pk_fma_f32 v[68:69], v[6:7], v[46:47], v[68:69]
	v_pk_fma_f32 v[64:65], v[8:9], v[32:33], v[64:65]
	v_pk_fma_f32 v[68:69], v[8:9], v[48:49], v[68:69]
	v_pk_fma_f32 v[64:65], v[10:11], v[34:35], v[64:65]
	v_pk_fma_f32 v[68:69], v[10:11], v[50:51], v[68:69]
	v_pk_fma_f32 v[64:65], v[12:13], v[36:37], v[64:65]
	v_pk_fma_f32 v[68:69], v[12:13], v[52:53], v[68:69]
	v_pk_fma_f32 v[64:65], v[14:15], v[38:39], v[64:65]
	v_pk_fma_f32 v[68:69], v[14:15], v[54:55], v[68:69]
	v_pk_fma_f32 v[64:65], v[16:17], v[40:41], v[64:65]
	v_pk_fma_f32 v[68:69], v[16:17], v[56:57], v[68:69]
	v_pk_mul_f32 v[114:115], v[2:3], v[58:59] op_sel_hi:[1,0]
	v_add_f32_e32 v63, v64, v65
	v_add_f32_e32 v72, v68, v69
	v_pk_mul_f32 v[116:117], v[4:5], v[58:59] op_sel_hi:[1,0]
	v_pk_mul_f32 v[118:119], v[6:7], v[58:59] op_sel_hi:[1,0]
	v_add_f32_dpp v63, v63, v63 quad_perm:[1,0,3,2] row_mask:0xf bank_mask:0xf bound_ctrl:1
	v_add_f32_dpp v72, v72, v72 quad_perm:[1,0,3,2] row_mask:0xf bank_mask:0xf bound_ctrl:1
	v_pk_mul_f32 v[120:121], v[8:9], v[58:59] op_sel_hi:[1,0]
	v_add_f32_dpp v63, v63, v63 quad_perm:[2,3,0,1] row_mask:0xf bank_mask:0xf bound_ctrl:1
	v_add_f32_dpp v72, v72, v72 quad_perm:[2,3,0,1] row_mask:0xf bank_mask:0xf bound_ctrl:1
	v_pk_mul_f32 v[122:123], v[10:11], v[58:59] op_sel_hi:[1,0]
	v_add_f32_dpp v63, v63, v63 row_half_mirror row_mask:0xf bank_mask:0xf bound_ctrl:1
	v_add_f32_dpp v72, v72, v72 row_half_mirror row_mask:0xf bank_mask:0xf bound_ctrl:1
	v_pk_mul_f32 v[124:125], v[12:13], v[58:59] op_sel_hi:[1,0]
	v_mul_f32_e32 v73, v63, v59
	v_pk_mul_f32 v[126:127], v[14:15], v[58:59] op_sel_hi:[1,0]
	v_fma_f32 v138, v62, v61, -v73
	v_pk_mul_f32 v[128:129], v[16:17], v[58:59] op_sel_hi:[1,0]
	v_pk_fma_f32 v[2:3], v[26:27], v[138:139], v[114:115] op_sel_hi:[1,0,1]
	v_mul_f32_e32 v113, v138, v60
	v_pk_fma_f32 v[4:5], v[28:29], v[138:139], v[116:117] op_sel_hi:[1,0,1]
	v_pk_fma_f32 v[6:7], v[30:31], v[138:139], v[118:119] op_sel_hi:[1,0,1]
	v_fma_f32 v137, v58, v72, v113
	v_pk_fma_f32 v[8:9], v[32:33], v[138:139], v[120:121] op_sel_hi:[1,0,1]
	v_pk_fma_f32 v[10:11], v[34:35], v[138:139], v[122:123] op_sel_hi:[1,0,1]
	ds_write_b32 v136, v137 offset:768
	v_pk_fma_f32 v[12:13], v[36:37], v[138:139], v[124:125] op_sel_hi:[1,0,1]
	v_pk_fma_f32 v[14:15], v[38:39], v[138:139], v[126:127] op_sel_hi:[1,0,1]
	v_pk_fma_f32 v[16:17], v[40:41], v[138:139], v[128:129] op_sel_hi:[1,0,1]
	ds_read_b128 v[26:29], v130 offset:11392
	ds_read_b128 v[30:33], v130 offset:11408
	ds_read_b128 v[34:37], v130 offset:11424
	ds_read_b128 v[38:41], v130 offset:11440
	ds_read_b128 v[42:45], v130 offset:12032
	ds_read_b128 v[46:49], v130 offset:12048
	ds_read_b128 v[50:53], v130 offset:12064
	ds_read_b128 v[54:57], v130 offset:12080
	ds_read_b32 v62, v132 offset:11392
	ds_read_b128 v[58:61], v133 offset:12800
	s_waitcnt lgkmcnt(10)
	v_pk_mul_f32 v[64:65], v[2:3], v[74:75]
	v_pk_mul_f32 v[68:69], v[2:3], v[92:93]
	v_pk_fma_f32 v[64:65], v[4:5], v[76:77], v[64:65]
	v_pk_fma_f32 v[68:69], v[4:5], v[94:95], v[68:69]
	v_pk_fma_f32 v[64:65], v[6:7], v[78:79], v[64:65]
	v_pk_fma_f32 v[68:69], v[6:7], v[96:97], v[68:69]
	v_pk_fma_f32 v[64:65], v[8:9], v[80:81], v[64:65]
	v_pk_fma_f32 v[68:69], v[8:9], v[98:99], v[68:69]
	v_pk_fma_f32 v[64:65], v[10:11], v[82:83], v[64:65]
	v_pk_fma_f32 v[68:69], v[10:11], v[100:101], v[68:69]
	v_pk_fma_f32 v[64:65], v[12:13], v[84:85], v[64:65]
	v_pk_fma_f32 v[68:69], v[12:13], v[102:103], v[68:69]
	v_pk_fma_f32 v[64:65], v[14:15], v[86:87], v[64:65]
	v_pk_fma_f32 v[68:69], v[14:15], v[104:105], v[68:69]
	v_pk_fma_f32 v[64:65], v[16:17], v[88:89], v[64:65]
	v_pk_fma_f32 v[68:69], v[16:17], v[106:107], v[68:69]
	v_pk_mul_f32 v[114:115], v[2:3], v[108:109] op_sel_hi:[1,0]
	v_add_f32_e32 v63, v64, v65
	v_add_f32_e32 v72, v68, v69
	v_pk_mul_f32 v[116:117], v[4:5], v[108:109] op_sel_hi:[1,0]
	v_pk_mul_f32 v[118:119], v[6:7], v[108:109] op_sel_hi:[1,0]
	v_add_f32_dpp v63, v63, v63 quad_perm:[1,0,3,2] row_mask:0xf bank_mask:0xf bound_ctrl:1
	v_add_f32_dpp v72, v72, v72 quad_perm:[1,0,3,2] row_mask:0xf bank_mask:0xf bound_ctrl:1
	v_pk_mul_f32 v[120:121], v[8:9], v[108:109] op_sel_hi:[1,0]
	v_add_f32_dpp v63, v63, v63 quad_perm:[2,3,0,1] row_mask:0xf bank_mask:0xf bound_ctrl:1
	v_add_f32_dpp v72, v72, v72 quad_perm:[2,3,0,1] row_mask:0xf bank_mask:0xf bound_ctrl:1
	v_pk_mul_f32 v[122:123], v[10:11], v[108:109] op_sel_hi:[1,0]
	v_add_f32_dpp v63, v63, v63 row_half_mirror row_mask:0xf bank_mask:0xf bound_ctrl:1
	v_add_f32_dpp v72, v72, v72 row_half_mirror row_mask:0xf bank_mask:0xf bound_ctrl:1
	v_pk_mul_f32 v[124:125], v[12:13], v[108:109] op_sel_hi:[1,0]
	v_mul_f32_e32 v73, v63, v109
	v_pk_mul_f32 v[126:127], v[14:15], v[108:109] op_sel_hi:[1,0]
	v_fma_f32 v138, v112, v111, -v73
	v_pk_mul_f32 v[128:129], v[16:17], v[108:109] op_sel_hi:[1,0]
	v_pk_fma_f32 v[2:3], v[74:75], v[138:139], v[114:115] op_sel_hi:[1,0,1]
	v_mul_f32_e32 v113, v138, v110
	v_pk_fma_f32 v[4:5], v[76:77], v[138:139], v[116:117] op_sel_hi:[1,0,1]
	v_pk_fma_f32 v[6:7], v[78:79], v[138:139], v[118:119] op_sel_hi:[1,0,1]
	v_fma_f32 v137, v108, v72, v113
	v_pk_fma_f32 v[8:9], v[80:81], v[138:139], v[120:121] op_sel_hi:[1,0,1]
	v_pk_fma_f32 v[10:11], v[82:83], v[138:139], v[122:123] op_sel_hi:[1,0,1]
	ds_write_b32 v136, v137 offset:896
	v_pk_fma_f32 v[12:13], v[84:85], v[138:139], v[124:125] op_sel_hi:[1,0,1]
	v_pk_fma_f32 v[14:15], v[86:87], v[138:139], v[126:127] op_sel_hi:[1,0,1]
	v_pk_fma_f32 v[16:17], v[88:89], v[138:139], v[128:129] op_sel_hi:[1,0,1]
	v_add_u32_e32 v130, 0x2c80, v130
	v_add_u32_e32 v132, 0x2c80, v132
	v_add_u32_e32 v133, 0x2c80, v133
	v_add_u32_e32 v136, 0x400, v136
	s_add_i32 s6, s6, 1
	s_cmp_eq_u32 s6, 4
	s_cbranch_scc0 .Lgd_step
	s_add_i32 s4, s4, 1
	s_xor_b64 s[0:1], s[0:1], -1
	s_cmpk_eq_i32 s4, 0x200
	s_waitcnt lgkmcnt(0)
	s_barrier
	s_cbranch_scc0 .LBB0_358
	s_branch .LBB0_172
